# NSA nsa_wg: hoist gate+oacc loads of the cmp/sel/window epilogues (was 4/4/16 serialized vmcnt(0) round trips) + sel-loop copy sink
# baseline (speedup 1.0000x reference)
.LBB0_2326:
	v_readlane_b32 s18, v254, 14
	v_readlane_b32 s19, v254, 15
	s_movk_i32 s16, 0xc0
	s_lshl_b32 s64, s47, 2
	v_mov_b64_e32 v[98:99], s[18:19]
	v_mad_i64_i32 v[98:99], s[16:17], v148, s16, v[98:99]
	s_mov_b32 s65, 0
	s_waitcnt vmcnt(1)
	v_lshl_add_u64 v[106:107], v[98:99], 0, s[64:65]
	global_load_dword v98, v[106:107], off
	global_load_dword v162, v[106:107], off offset:4
	global_load_dword v164, v[106:107], off offset:8
	global_load_dword v166, v[106:107], off offset:12
	v_readlane_b32 s16, v254, 16
	s_waitcnt vmcnt(1)
	v_lshlrev_b64 v[100:101], 12, v[148:149]
	v_lshlrev_b32_e32 v116, 2, v160
	v_readlane_b32 s17, v254, 17
	v_ashrrev_i32_e32 v117, 31, v116
	s_lshl_b32 s68, s45, 2
	v_lshl_add_u64 v[100:101], s[16:17], 0, v[100:101]
	s_mov_b32 s69, s65
	v_lshl_add_u64 v[100:101], v[116:117], 2, v[100:101]
	v_lshl_add_u64 v[114:115], v[100:101], 0, s[68:69]
	s_lshl_b32 s70, s43, 2
	s_mov_b32 s71, s65
	v_lshl_add_u64 v[112:113], v[100:101], 0, s[70:71]
	s_lshl_b32 s72, s42, 2
	s_mov_b32 s73, s65
	v_lshl_add_u64 v[110:111], v[100:101], 0, s[72:73]
	s_lshl_b32 s66, s41, 2
	s_mov_b32 s67, s65
	s_ashr_i32 s46, s24, 6
	v_lshl_add_u64 v[108:109], v[100:101], 0, s[66:67]
	s_add_i32 s48, s46, -1
	v_cmp_gt_u32_e32 vcc, 16, v158
	s_waitcnt vmcnt(3)
	v_pk_mul_f32 v[96:97], v[96:97], v[98:99] op_sel_hi:[1,0]
	v_pk_mul_f32 v[94:95], v[94:95], v[98:99] op_sel_hi:[1,0]
	v_pk_mul_f32 v[92:93], v[92:93], v[98:99] op_sel_hi:[1,0]
	v_pk_mul_f32 v[90:91], v[90:91], v[98:99] op_sel_hi:[1,0]
	v_pk_mul_f32 v[88:89], v[88:89], v[98:99] op_sel_hi:[1,0]
	v_pk_mul_f32 v[86:87], v[86:87], v[98:99] op_sel_hi:[1,0]
	v_pk_mul_f32 v[84:85], v[84:85], v[98:99] op_sel_hi:[1,0]
	v_pk_mul_f32 v[82:83], v[82:83], v[98:99] op_sel_hi:[1,0]
	global_store_dwordx4 v[114:115], v[94:97], off
	global_store_dwordx4 v[114:115], v[90:93], off offset:64
	global_store_dwordx4 v[114:115], v[86:89], off offset:128
	global_store_dwordx4 v[114:115], v[82:85], off offset:192
	s_waitcnt vmcnt(6)
	v_pk_mul_f32 v[80:81], v[80:81], v[162:163] op_sel_hi:[1,0]
	v_pk_mul_f32 v[78:79], v[78:79], v[162:163] op_sel_hi:[1,0]
	v_pk_mul_f32 v[76:77], v[76:77], v[162:163] op_sel_hi:[1,0]
	v_pk_mul_f32 v[74:75], v[74:75], v[162:163] op_sel_hi:[1,0]
	v_pk_mul_f32 v[72:73], v[72:73], v[162:163] op_sel_hi:[1,0]
	v_pk_mul_f32 v[70:71], v[70:71], v[162:163] op_sel_hi:[1,0]
	v_pk_mul_f32 v[68:69], v[68:69], v[162:163] op_sel_hi:[1,0]
	v_pk_mul_f32 v[66:67], v[66:67], v[162:163] op_sel_hi:[1,0]
	global_store_dwordx4 v[112:113], v[78:81], off
	global_store_dwordx4 v[112:113], v[74:77], off offset:64
	global_store_dwordx4 v[112:113], v[70:73], off offset:128
	global_store_dwordx4 v[112:113], v[66:69], off offset:192
	s_waitcnt vmcnt(9)
	v_pk_mul_f32 v[64:65], v[64:65], v[164:165] op_sel_hi:[1,0]
	v_pk_mul_f32 v[62:63], v[62:63], v[164:165] op_sel_hi:[1,0]
	v_pk_mul_f32 v[60:61], v[60:61], v[164:165] op_sel_hi:[1,0]
	v_pk_mul_f32 v[58:59], v[58:59], v[164:165] op_sel_hi:[1,0]
	v_pk_mul_f32 v[56:57], v[56:57], v[164:165] op_sel_hi:[1,0]
	v_pk_mul_f32 v[54:55], v[54:55], v[164:165] op_sel_hi:[1,0]
	v_pk_mul_f32 v[52:53], v[52:53], v[164:165] op_sel_hi:[1,0]
	v_pk_mul_f32 v[50:51], v[50:51], v[164:165] op_sel_hi:[1,0]
	global_store_dwordx4 v[110:111], v[62:65], off
	global_store_dwordx4 v[110:111], v[58:61], off offset:64
	global_store_dwordx4 v[110:111], v[54:57], off offset:128
	global_store_dwordx4 v[110:111], v[50:53], off offset:192
	s_waitcnt vmcnt(12)
	v_pk_mul_f32 v[48:49], v[48:49], v[166:167] op_sel_hi:[1,0]
	v_pk_mul_f32 v[46:47], v[46:47], v[166:167] op_sel_hi:[1,0]
	v_lshlrev_b32_e32 v50, 5, v160
	v_pk_mul_f32 v[44:45], v[44:45], v[166:167] op_sel_hi:[1,0]
	v_pk_mul_f32 v[42:43], v[42:43], v[166:167] op_sel_hi:[1,0]
	v_pk_mul_f32 v[40:41], v[40:41], v[166:167] op_sel_hi:[1,0]
	v_pk_mul_f32 v[38:39], v[38:39], v[166:167] op_sel_hi:[1,0]
	v_pk_mul_f32 v[36:37], v[36:37], v[166:167] op_sel_hi:[1,0]
	v_pk_mul_f32 v[34:35], v[34:35], v[166:167] op_sel_hi:[1,0]
	global_store_dwordx4 v[108:109], v[46:49], off
	global_store_dwordx4 v[108:109], v[42:45], off offset:64
	global_store_dwordx4 v[108:109], v[38:41], off offset:128
	global_store_dwordx4 v[108:109], v[34:37], off offset:192
	s_waitcnt lgkmcnt(0)
	v_cmp_eq_u32_e64 s[16:17], s46, v50
	v_cmp_eq_u32_e64 s[18:19], s48, v50
	s_or_b64 s[16:17], s[16:17], s[18:19]
	s_nor_b64 s[16:17], vcc, s[16:17]
	s_and_saveexec_b64 s[18:19], s[16:17]
	s_xor_b64 s[18:19], exec, s[18:19]
	s_cbranch_execz .LBB0_2328
	v_lshl_add_u32 v1, v50, 2, v125
	ds_read_b32 v1, v1
	v_sub_u32_e32 v34, 0x7f, v50
	s_movk_i32 s16, 0xff80
	s_waitcnt lgkmcnt(0)
	v_and_or_b32 v1, v1, s16, v34
	v_add_u32_e32 v1, 0x80, v1
	v_cmp_ge_i32_e64 s[16:17], s46, v50
	s_nop 1
	v_cndmask_b32_e64 v37, 0, v1, s[16:17]

.LBB0_2486:
	v_mov_b32_e32 v1, v123
	s_nop 1
	v_permlane16_swap_b32 v123, v1
	v_mov_b32_e32 v53, v122
	v_add_f32_e32 v1, v123, v1
	v_mov_b32_e32 v50, v1
	s_nop 1
	v_permlane32_swap_b32 v1, v50
	global_load_dword v51, v[106:107], off offset:64
	global_load_dwordx4 v[34:37], v[114:115], off
	global_load_dwordx4 v[38:41], v[114:115], off offset:64
	global_load_dwordx4 v[42:45], v[114:115], off offset:128
	global_load_dwordx4 v[46:49], v[114:115], off offset:192
	global_load_dword v90, v[106:107], off offset:68
	global_load_dwordx4 v[58:61], v[112:113], off
	global_load_dwordx4 v[62:65], v[112:113], off offset:64
	global_load_dwordx4 v[66:69], v[112:113], off offset:128
	global_load_dwordx4 v[70:73], v[112:113], off offset:192
	global_load_dword v91, v[106:107], off offset:72
	global_load_dwordx4 v[74:77], v[110:111], off
	global_load_dwordx4 v[78:81], v[110:111], off offset:64
	global_load_dwordx4 v[82:85], v[110:111], off offset:128
	global_load_dwordx4 v[86:89], v[110:111], off offset:192
	global_load_dword v92, v[106:107], off offset:76
	global_load_dwordx4 v[236:239], v[108:109], off
	global_load_dwordx4 v[240:243], v[108:109], off offset:64
	global_load_dwordx4 v[244:247], v[108:109], off offset:128
	global_load_dwordx4 v[248:251], v[108:109], off offset:192
	v_add_f32_e32 v1, v1, v50
	v_max_f32_e32 v1, 0xda24260, v1
	s_waitcnt vmcnt(19)
	v_div_scale_f32 v50, s[16:17], v1, v1, v51
	v_rcp_f32_e32 v52, v50
	v_div_scale_f32 v54, vcc, v51, v1, v51
	v_fma_f32 v55, -v50, v52, 1.0
	v_fmac_f32_e32 v52, v55, v52
	v_mul_f32_e32 v55, v54, v52
	v_fma_f32 v56, -v50, v55, v54
	v_fmac_f32_e32 v55, v56, v52
	v_fma_f32 v50, -v50, v55, v54
	v_div_fmas_f32 v50, v50, v52, v55
	v_div_fixup_f32 v50, v50, v1, v51
	s_waitcnt vmcnt(18)
	v_pk_fma_f32 v[36:37], v[198:199], v[50:51], v[36:37] op_sel_hi:[1,0,1]
	v_pk_fma_f32 v[34:35], v[200:201], v[50:51], v[34:35] op_sel_hi:[1,0,1]
	s_waitcnt vmcnt(17)
	v_pk_fma_f32 v[40:41], v[202:203], v[50:51], v[40:41] op_sel_hi:[1,0,1]
	v_pk_fma_f32 v[38:39], v[204:205], v[50:51], v[38:39] op_sel_hi:[1,0,1]
	s_waitcnt vmcnt(16)
	v_pk_fma_f32 v[44:45], v[206:207], v[50:51], v[44:45] op_sel_hi:[1,0,1]
	v_pk_fma_f32 v[42:43], v[208:209], v[50:51], v[42:43] op_sel_hi:[1,0,1]
	s_waitcnt vmcnt(15)
	v_pk_fma_f32 v[48:49], v[210:211], v[50:51], v[48:49] op_sel_hi:[1,0,1]
	v_pk_fma_f32 v[46:47], v[212:213], v[50:51], v[46:47] op_sel_hi:[1,0,1]
	global_store_dwordx4 v[114:115], v[34:37], off
	global_store_dwordx4 v[114:115], v[38:41], off offset:64
	global_store_dwordx4 v[114:115], v[42:45], off offset:128
	global_store_dwordx4 v[114:115], v[46:49], off offset:192
	s_nop 1
	v_permlane16_swap_b32 v122, v53
	s_nop 0
	v_add_f32_e32 v1, v122, v53
	v_mov_b32_e32 v50, v1
	s_nop 1
	v_permlane32_swap_b32 v50, v1
	v_add_f32_e32 v1, v50, v1
	v_max_f32_e32 v1, 0xda24260, v1
	v_mov_b32_e32 v53, v121
	s_waitcnt vmcnt(18)
	v_div_scale_f32 v50, s[16:17], v1, v1, v90
	v_rcp_f32_e32 v52, v50
	v_div_scale_f32 v54, vcc, v90, v1, v90
	v_fma_f32 v55, -v50, v52, 1.0
	v_fmac_f32_e32 v52, v55, v52
	v_mul_f32_e32 v55, v54, v52
	v_fma_f32 v56, -v50, v55, v54
	v_fmac_f32_e32 v55, v56, v52
	v_fma_f32 v50, -v50, v55, v54
	v_div_fmas_f32 v50, v50, v52, v55
	v_div_fixup_f32 v50, v50, v1, v90
	s_waitcnt vmcnt(17)
	v_pk_fma_f32 v[36:37], v[182:183], v[50:51], v[60:61] op_sel_hi:[1,0,1]
	v_pk_fma_f32 v[34:35], v[184:185], v[50:51], v[58:59] op_sel_hi:[1,0,1]
	s_waitcnt vmcnt(16)
	v_pk_fma_f32 v[40:41], v[186:187], v[50:51], v[64:65] op_sel_hi:[1,0,1]
	v_pk_fma_f32 v[38:39], v[188:189], v[50:51], v[62:63] op_sel_hi:[1,0,1]
	s_waitcnt vmcnt(15)
	v_pk_fma_f32 v[44:45], v[190:191], v[50:51], v[68:69] op_sel_hi:[1,0,1]
	v_pk_fma_f32 v[42:43], v[192:193], v[50:51], v[66:67] op_sel_hi:[1,0,1]
	s_waitcnt vmcnt(14)
	v_pk_fma_f32 v[48:49], v[194:195], v[50:51], v[72:73] op_sel_hi:[1,0,1]
	v_pk_fma_f32 v[46:47], v[196:197], v[50:51], v[70:71] op_sel_hi:[1,0,1]
	global_store_dwordx4 v[112:113], v[34:37], off
	global_store_dwordx4 v[112:113], v[38:41], off offset:64
	global_store_dwordx4 v[112:113], v[42:45], off offset:128
	global_store_dwordx4 v[112:113], v[46:49], off offset:192
	s_nop 1
	v_permlane16_swap_b32 v121, v53
	s_nop 0
	v_add_f32_e32 v1, v121, v53
	v_mov_b32_e32 v50, v1
	s_nop 1
	v_permlane32_swap_b32 v50, v1
	v_add_f32_e32 v1, v50, v1
	v_max_f32_e32 v1, 0xda24260, v1
	v_mov_b32_e32 v53, v120
	s_waitcnt vmcnt(17)
	v_div_scale_f32 v50, s[16:17], v1, v1, v91
	v_rcp_f32_e32 v52, v50
	v_div_scale_f32 v54, vcc, v91, v1, v91
	s_max_i32 s17, s27, 0x1ff
	v_fma_f32 v55, -v50, v52, 1.0
	v_fmac_f32_e32 v52, v55, v52
	v_mul_f32_e32 v55, v54, v52
	v_fma_f32 v56, -v50, v55, v54
	v_fmac_f32_e32 v55, v56, v52
	v_fma_f32 v50, -v50, v55, v54
	v_div_fmas_f32 v50, v50, v52, v55
	v_div_fixup_f32 v50, v50, v1, v91
	s_waitcnt vmcnt(16)
	v_pk_fma_f32 v[36:37], v[176:177], v[50:51], v[76:77] op_sel_hi:[1,0,1]
	v_pk_fma_f32 v[34:35], v[178:179], v[50:51], v[74:75] op_sel_hi:[1,0,1]
	s_waitcnt vmcnt(15)
	v_pk_fma_f32 v[40:41], v[172:173], v[50:51], v[80:81] op_sel_hi:[1,0,1]
	v_pk_fma_f32 v[38:39], v[174:175], v[50:51], v[78:79] op_sel_hi:[1,0,1]
	s_waitcnt vmcnt(14)
	v_pk_fma_f32 v[44:45], v[168:169], v[50:51], v[84:85] op_sel_hi:[1,0,1]
	v_pk_fma_f32 v[42:43], v[170:171], v[50:51], v[82:83] op_sel_hi:[1,0,1]
	s_waitcnt vmcnt(13)
	v_pk_fma_f32 v[48:49], v[164:165], v[50:51], v[88:89] op_sel_hi:[1,0,1]
	v_pk_fma_f32 v[46:47], v[166:167], v[50:51], v[86:87] op_sel_hi:[1,0,1]
	global_store_dwordx4 v[110:111], v[34:37], off
	global_store_dwordx4 v[110:111], v[38:41], off offset:64
	global_store_dwordx4 v[110:111], v[42:45], off offset:128
	global_store_dwordx4 v[110:111], v[46:49], off offset:192
	s_nop 1
	v_permlane16_swap_b32 v120, v53
	s_lshl_b32 s16, s25, 1
	v_add_f32_e32 v1, v120, v53
	v_mov_b32_e32 v50, v1
	s_nop 1
	v_permlane32_swap_b32 v1, v50
	s_addk_i32 s17, 0xfe01
	v_add_f32_e32 v1, v1, v50
	s_or_b32 s18, s16, 1
	s_lshr_b32 s25, s17, 6
	v_max_f32_e32 v1, 0xda24260, v1
	s_sub_i32 s27, s18, s25
	s_cmp_gt_i32 s27, -1
	s_waitcnt vmcnt(16)
	v_div_scale_f32 v50, s[18:19], v1, v1, v92
	v_rcp_f32_e32 v52, v50
	v_div_scale_f32 v53, vcc, v92, v1, v92
	v_fma_f32 v54, -v50, v52, 1.0
	v_fmac_f32_e32 v52, v54, v52
	v_mul_f32_e32 v54, v53, v52
	v_fma_f32 v55, -v50, v54, v53
	v_fmac_f32_e32 v54, v55, v52
	v_fma_f32 v50, -v50, v54, v53
	v_div_fmas_f32 v50, v50, v52, v54
	v_div_fixup_f32 v50, v50, v1, v92
	s_waitcnt vmcnt(15)
	v_pk_fma_f32 v[36:37], v[160:161], v[50:51], v[238:239] op_sel_hi:[1,0,1]
	v_pk_fma_f32 v[34:35], v[162:163], v[50:51], v[236:237] op_sel_hi:[1,0,1]
	s_waitcnt vmcnt(14)
	v_pk_fma_f32 v[40:41], v[156:157], v[50:51], v[242:243] op_sel_hi:[1,0,1]
	v_pk_fma_f32 v[38:39], v[158:159], v[50:51], v[240:241] op_sel_hi:[1,0,1]
	s_waitcnt vmcnt(13)
	v_pk_fma_f32 v[44:45], v[152:153], v[50:51], v[246:247] op_sel_hi:[1,0,1]
	v_pk_fma_f32 v[42:43], v[154:155], v[50:51], v[244:245] op_sel_hi:[1,0,1]
	s_waitcnt vmcnt(12)
	v_pk_fma_f32 v[48:49], v[148:149], v[50:51], v[250:251] op_sel_hi:[1,0,1]
	v_pk_fma_f32 v[46:47], v[150:151], v[50:51], v[248:249] op_sel_hi:[1,0,1]
	global_store_dwordx4 v[108:109], v[34:37], off
	global_store_dwordx4 v[108:109], v[38:41], off offset:64
	global_store_dwordx4 v[108:109], v[42:45], off offset:128
	global_store_dwordx4 v[108:109], v[46:49], off offset:192
	s_cbranch_scc0 .LBB0_2488
	s_and_b32 s18, s17, 0xffffffc0
	v_or_b32_e32 v34, s18, v214
	v_mov_b32_e32 v35, 0
	v_lshlrev_b64 v[36:37], 7, v[34:35]
	s_mov_b32 s19, 0
	v_lshl_add_u64 v[36:37], s[22:23], 0, v[36:37]
	v_mov_b32_e32 v131, v35
	v_lshl_add_u64 v[34:35], v[36:37], 0, v[130:131]
	v_lshl_add_u64 v[36:37], s[18:19], 1, v[132:133]
	v_lshl_add_u64 v[38:39], v[36:37], 0, v[130:131]
	global_load_dwordx4 v[34:37], v[34:35], off
	s_nop 0
	global_load_dwordx4 v[38:41], v[38:39], off
	s_waitcnt vmcnt(1)
	ds_write_b128 v230, v[34:37]
	s_waitcnt vmcnt(0)
	ds_write_b128 v231, v[38:41]

.LBB0_2502:
	global_load_dword v98, v[106:107], off offset:128
	global_load_dword v99, v[106:107], off offset:132
	global_load_dword v100, v[106:107], off offset:136
	global_load_dword v101, v[106:107], off offset:140
	global_load_dwordx4 v[164:167], v[114:115], off
	global_load_dwordx4 v[168:171], v[114:115], off offset:64
	global_load_dwordx4 v[172:175], v[114:115], off offset:128
	global_load_dwordx4 v[176:179], v[114:115], off offset:192
	global_load_dwordx4 v[180:183], v[112:113], off
	global_load_dwordx4 v[184:187], v[112:113], off offset:64
	global_load_dwordx4 v[188:191], v[112:113], off offset:128
	global_load_dwordx4 v[192:195], v[112:113], off offset:192
	global_load_dwordx4 v[196:199], v[110:111], off
	global_load_dwordx4 v[200:203], v[110:111], off offset:64
	global_load_dwordx4 v[204:207], v[110:111], off offset:128
	global_load_dwordx4 v[208:211], v[110:111], off offset:192
	global_load_dwordx4 v[228:231], v[108:109], off
	global_load_dwordx4 v[232:235], v[108:109], off offset:64
	global_load_dwordx4 v[236:239], v[108:109], off offset:128
	global_load_dwordx4 v[240:243], v[108:109], off offset:192
	v_mov_b32_e32 v1, v2
	s_nop 1
	v_permlane16_swap_b32 v2, v1
	v_readlane_b32 s16, v254, 12
	v_add_f32_e32 v1, v2, v1
	v_mov_b32_e32 v8, v1
	s_nop 1
	v_permlane32_swap_b32 v1, v8
	v_add_f32_e32 v1, v1, v8
	v_readlane_b32 s17, v254, 13
	v_max_f32_e32 v1, 0xda24260, v1
	s_mov_b32 s57, 0
	v_lshl_add_u64 v[2:3], v[118:119], 1, s[16:17]
	v_lshl_add_u64 v[2:3], v[116:117], 1, v[2:3]
	v_lshl_add_u64 v[8:9], v[2:3], 0, s[56:57]
	s_mov_b32 s63, s57
	s_mov_b32 s61, s57
	s_mov_b32 s59, s57
	s_sub_i32 s25, 0x4f, s39
	s_lshl_b32 s27, s25, 7
	v_mov_b32_e32 v158, v146
	s_add_i32 s24, s3, s27
	v_mov_b32_e32 v131, 0
	s_waitcnt vmcnt(16)
	v_div_scale_f32 v11, s[16:17], v1, v1, v98
	v_rcp_f32_e32 v12, v11
	v_div_scale_f32 v13, vcc, v98, v1, v98
	v_fma_f32 v14, -v11, v12, 1.0
	v_fmac_f32_e32 v12, v14, v12
	v_mul_f32_e32 v14, v13, v12
	v_fma_f32 v15, -v11, v14, v13
	v_fmac_f32_e32 v14, v15, v12
	v_fma_f32 v11, -v11, v14, v13
	v_div_fmas_f32 v11, v11, v12, v14
	v_div_fixup_f32 v10, v11, v1, v98
	s_waitcnt vmcnt(15)
	v_pk_fma_f32 v[6:7], v[96:97], v[10:11], v[166:167] op_sel_hi:[1,0,1]
	v_pk_fma_f32 v[4:5], v[94:95], v[10:11], v[164:165] op_sel_hi:[1,0,1]
	v_mov_b32_e32 v1, v122
	v_cvt_pk_bf16_f32 v4, v4, v5
	v_cvt_pk_bf16_f32 v5, v6, v7
	global_store_dwordx2 v[8:9], v[4:5], off
	s_waitcnt vmcnt(15)
	v_pk_fma_f32 v[6:7], v[92:93], v[10:11], v[170:171] op_sel_hi:[1,0,1]
	v_pk_fma_f32 v[4:5], v[90:91], v[10:11], v[168:169] op_sel_hi:[1,0,1]
	s_nop 0
	v_cvt_pk_bf16_f32 v4, v4, v5
	v_cvt_pk_bf16_f32 v5, v6, v7
	global_store_dwordx2 v[8:9], v[4:5], off offset:32
	s_waitcnt vmcnt(15)
	v_pk_fma_f32 v[6:7], v[88:89], v[10:11], v[174:175] op_sel_hi:[1,0,1]
	v_pk_fma_f32 v[4:5], v[86:87], v[10:11], v[172:173] op_sel_hi:[1,0,1]
	s_nop 0
	v_cvt_pk_bf16_f32 v4, v4, v5
	v_cvt_pk_bf16_f32 v5, v6, v7
	global_store_dwordx2 v[8:9], v[4:5], off offset:64
	s_waitcnt vmcnt(15)
	v_pk_fma_f32 v[6:7], v[84:85], v[10:11], v[178:179] op_sel_hi:[1,0,1]
	v_pk_fma_f32 v[4:5], v[82:83], v[10:11], v[176:177] op_sel_hi:[1,0,1]
	s_nop 0
	v_cvt_pk_bf16_f32 v4, v4, v5
	v_cvt_pk_bf16_f32 v5, v6, v7
	global_store_dwordx2 v[8:9], v[4:5], off offset:96
	s_nop 1
	v_permlane16_swap_b32 v122, v1
	s_nop 0
	v_add_f32_e32 v1, v122, v1
	v_mov_b32_e32 v8, v1
	s_nop 1
	v_permlane32_swap_b32 v8, v1
	v_add_f32_e32 v1, v8, v1
	v_max_f32_e32 v1, 0xda24260, v1
	v_lshl_add_u64 v[8:9], v[2:3], 0, s[62:63]
	s_waitcnt vmcnt(16)
	v_div_scale_f32 v11, s[16:17], v1, v1, v99
	v_rcp_f32_e32 v12, v11
	v_div_scale_f32 v13, vcc, v99, v1, v99
	v_fma_f32 v14, -v11, v12, 1.0
	v_fmac_f32_e32 v12, v14, v12
	v_mul_f32_e32 v14, v13, v12
	v_fma_f32 v15, -v11, v14, v13
	v_fmac_f32_e32 v14, v15, v12
	v_fma_f32 v11, -v11, v14, v13
	v_div_fmas_f32 v11, v11, v12, v14
	v_div_fixup_f32 v10, v11, v1, v99
	s_waitcnt vmcnt(15)
	v_pk_fma_f32 v[6:7], v[80:81], v[10:11], v[182:183] op_sel_hi:[1,0,1]
	v_pk_fma_f32 v[4:5], v[78:79], v[10:11], v[180:181] op_sel_hi:[1,0,1]
	v_mov_b32_e32 v1, v121
	v_cvt_pk_bf16_f32 v4, v4, v5
	v_cvt_pk_bf16_f32 v5, v6, v7
	global_store_dwordx2 v[8:9], v[4:5], off
	s_waitcnt vmcnt(15)
	v_pk_fma_f32 v[6:7], v[76:77], v[10:11], v[186:187] op_sel_hi:[1,0,1]
	v_pk_fma_f32 v[4:5], v[74:75], v[10:11], v[184:185] op_sel_hi:[1,0,1]
	s_nop 0
	v_cvt_pk_bf16_f32 v4, v4, v5
	v_cvt_pk_bf16_f32 v5, v6, v7
	global_store_dwordx2 v[8:9], v[4:5], off offset:32
	s_waitcnt vmcnt(15)
	v_pk_fma_f32 v[6:7], v[72:73], v[10:11], v[190:191] op_sel_hi:[1,0,1]
	v_pk_fma_f32 v[4:5], v[70:71], v[10:11], v[188:189] op_sel_hi:[1,0,1]
	s_nop 0
	v_cvt_pk_bf16_f32 v4, v4, v5
	v_cvt_pk_bf16_f32 v5, v6, v7
	global_store_dwordx2 v[8:9], v[4:5], off offset:64
	s_waitcnt vmcnt(15)
	v_pk_fma_f32 v[6:7], v[68:69], v[10:11], v[194:195] op_sel_hi:[1,0,1]
	v_pk_fma_f32 v[4:5], v[66:67], v[10:11], v[192:193] op_sel_hi:[1,0,1]
	s_nop 0
	v_cvt_pk_bf16_f32 v4, v4, v5
	v_cvt_pk_bf16_f32 v5, v6, v7
	global_store_dwordx2 v[8:9], v[4:5], off offset:96
	s_nop 1
	v_permlane16_swap_b32 v121, v1
	s_nop 0
	v_add_f32_e32 v1, v121, v1
	v_mov_b32_e32 v8, v1
	s_nop 1
	v_permlane32_swap_b32 v8, v1
	v_add_f32_e32 v1, v8, v1
	v_max_f32_e32 v1, 0xda24260, v1
	v_lshl_add_u64 v[8:9], v[2:3], 0, s[60:61]
	s_waitcnt vmcnt(16)
	v_div_scale_f32 v11, s[16:17], v1, v1, v100
	v_rcp_f32_e32 v12, v11
	v_div_scale_f32 v13, vcc, v100, v1, v100
	v_fma_f32 v14, -v11, v12, 1.0
	v_fmac_f32_e32 v12, v14, v12
	v_mul_f32_e32 v14, v13, v12
	v_fma_f32 v15, -v11, v14, v13
	v_fmac_f32_e32 v14, v15, v12
	v_fma_f32 v11, -v11, v14, v13
	v_div_fmas_f32 v11, v11, v12, v14
	v_div_fixup_f32 v10, v11, v1, v100
	s_waitcnt vmcnt(15)
	v_pk_fma_f32 v[6:7], v[64:65], v[10:11], v[198:199] op_sel_hi:[1,0,1]
	v_pk_fma_f32 v[4:5], v[62:63], v[10:11], v[196:197] op_sel_hi:[1,0,1]
	v_mov_b32_e32 v1, v120
	v_cvt_pk_bf16_f32 v4, v4, v5
	v_cvt_pk_bf16_f32 v5, v6, v7
	global_store_dwordx2 v[8:9], v[4:5], off
	s_waitcnt vmcnt(15)
	v_pk_fma_f32 v[6:7], v[60:61], v[10:11], v[202:203] op_sel_hi:[1,0,1]
	v_pk_fma_f32 v[4:5], v[58:59], v[10:11], v[200:201] op_sel_hi:[1,0,1]
	s_nop 0
	v_cvt_pk_bf16_f32 v4, v4, v5
	v_cvt_pk_bf16_f32 v5, v6, v7
	global_store_dwordx2 v[8:9], v[4:5], off offset:32
	s_waitcnt vmcnt(15)
	v_pk_fma_f32 v[6:7], v[56:57], v[10:11], v[206:207] op_sel_hi:[1,0,1]
	v_pk_fma_f32 v[4:5], v[54:55], v[10:11], v[204:205] op_sel_hi:[1,0,1]
	s_nop 0
	v_cvt_pk_bf16_f32 v4, v4, v5
	v_cvt_pk_bf16_f32 v5, v6, v7
	global_store_dwordx2 v[8:9], v[4:5], off offset:64
	s_waitcnt vmcnt(15)
	v_pk_fma_f32 v[6:7], v[52:53], v[10:11], v[210:211] op_sel_hi:[1,0,1]
	v_pk_fma_f32 v[4:5], v[50:51], v[10:11], v[208:209] op_sel_hi:[1,0,1]
	s_nop 0
	v_cvt_pk_bf16_f32 v4, v4, v5
	v_cvt_pk_bf16_f32 v5, v6, v7
	global_store_dwordx2 v[8:9], v[4:5], off offset:96
	s_nop 1
	v_permlane16_swap_b32 v120, v1
	s_nop 0
	v_add_f32_e32 v1, v120, v1
	v_mov_b32_e32 v8, v1
	s_nop 1
	v_permlane32_swap_b32 v1, v8
	v_add_f32_e32 v1, v1, v8
	v_max_f32_e32 v1, 0xda24260, v1
	v_lshl_add_u64 v[8:9], v[2:3], 0, s[58:59]
	s_waitcnt vmcnt(16)
	v_div_scale_f32 v11, s[16:17], v1, v1, v101
	v_rcp_f32_e32 v12, v11
	v_div_scale_f32 v2, vcc, v101, v1, v101
	s_add_i32 s16, s24, s37
	v_fma_f32 v3, -v11, v12, 1.0
	v_fmac_f32_e32 v12, v3, v12
	v_mul_f32_e32 v3, v2, v12
	v_fma_f32 v13, -v11, v3, v2
	v_fmac_f32_e32 v3, v13, v12
	v_fma_f32 v2, -v11, v3, v2
	v_div_fmas_f32 v2, v2, v12, v3
	v_div_fixup_f32 v10, v2, v1, v101
	s_waitcnt vmcnt(15)
	v_pk_fma_f32 v[2:3], v[48:49], v[10:11], v[230:231] op_sel_hi:[1,0,1]
	v_pk_fma_f32 v[4:5], v[46:47], v[10:11], v[228:229] op_sel_hi:[1,0,1]
	v_mov_b32_e32 v1, 0
	v_cvt_pk_bf16_f32 v4, v4, v5
	v_cvt_pk_bf16_f32 v5, v2, v3
	global_store_dwordx2 v[8:9], v[4:5], off
	s_waitcnt vmcnt(15)
	v_pk_fma_f32 v[4:5], v[44:45], v[10:11], v[234:235] op_sel_hi:[1,0,1]
	v_pk_fma_f32 v[2:3], v[42:43], v[10:11], v[232:233] op_sel_hi:[1,0,1]
	s_nop 0
	v_cvt_pk_bf16_f32 v2, v2, v3
	v_cvt_pk_bf16_f32 v3, v4, v5
	global_store_dwordx2 v[8:9], v[2:3], off offset:32
	s_waitcnt vmcnt(15)
	v_pk_fma_f32 v[4:5], v[40:41], v[10:11], v[238:239] op_sel_hi:[1,0,1]
	v_pk_fma_f32 v[2:3], v[38:39], v[10:11], v[236:237] op_sel_hi:[1,0,1]
	s_nop 0
	v_cvt_pk_bf16_f32 v2, v2, v3
	v_cvt_pk_bf16_f32 v3, v4, v5
	global_store_dwordx2 v[8:9], v[2:3], off offset:64
	s_waitcnt vmcnt(15)
	v_pk_fma_f32 v[4:5], v[36:37], v[10:11], v[242:243] op_sel_hi:[1,0,1]
	v_pk_fma_f32 v[2:3], v[34:35], v[10:11], v[240:241] op_sel_hi:[1,0,1]
	s_nop 0
	v_cvt_pk_bf16_f32 v2, v2, v3
	v_cvt_pk_bf16_f32 v3, v4, v5
	global_store_dwordx2 v[8:9], v[2:3], off offset:96
	s_barrier
	s_nop 0
	v_and_b32_e32 v226, 15, v158
	v_or_b32_e32 v148, s16, v226
	v_ashrrev_i32_e32 v160, 4, v158
	v_ashrrev_i32_e32 v149, 31, v148
	v_lshlrev_b32_e32 v144, 3, v160
	v_lshlrev_b64 v[2:3], 11, v[148:149]
	v_ashrrev_i32_e32 v145, 31, v144
	v_lshl_add_u64 v[2:3], s[54:55], 0, v[2:3]
	v_lshl_add_u64 v[2:3], v[144:145], 1, v[2:3]
	v_lshl_add_u64 v[6:7], v[2:3], 0, s[56:57]
	v_lshl_add_u64 v[14:15], v[2:3], 0, s[62:63]
	v_lshl_add_u64 v[22:23], v[2:3], 0, s[60:61]
	v_lshl_add_u64 v[30:31], v[2:3], 0, s[58:59]
	global_load_dwordx4 v[2:5], v[6:7], off
	s_nop 0
	global_load_dwordx4 v[6:9], v[6:7], off offset:64
	s_nop 0
	global_load_dwordx4 v[10:13], v[14:15], off
	s_nop 0
	global_load_dwordx4 v[14:17], v[14:15], off offset:64
	s_nop 0
	global_load_dwordx4 v[18:21], v[22:23], off
	s_nop 0
	global_load_dwordx4 v[22:25], v[22:23], off offset:64
	s_nop 0
	global_load_dwordx4 v[26:29], v[30:31], off
	s_nop 0
	global_load_dwordx4 v[30:33], v[30:31], off offset:64
	s_movk_i32 s16, 0x840
	v_cmp_gt_i32_e32 vcc, s16, v158
	s_and_saveexec_b64 s[16:17], vcc
	s_cbranch_execz .LBB0_2505
	v_lshlrev_b32_e32 v35, 2, v158
	v_readlane_b32 s18, v254, 60
	v_subrev_u32_e32 v34, 64, v158
	s_movk_i32 s20, 0x7ff
	v_add3_u32 v35, s18, v35, v131
	s_mov_b64 s[18:19], 0

.LBB0_2538:
	v_readlane_b32 s18, v254, 14
	v_readlane_b32 s19, v254, 15
	s_movk_i32 s16, 0xc0
	s_mov_b32 s65, 0
	v_mov_b64_e32 v[98:99], s[18:19]
	v_mad_i64_i32 v[98:99], s[16:17], v148, s16, v[98:99]
	s_waitcnt vmcnt(1)
	v_lshl_add_u64 v[106:107], v[98:99], 0, s[64:65]
	global_load_dword v98, v[106:107], off
	global_load_dword v162, v[106:107], off offset:4
	global_load_dword v164, v[106:107], off offset:8
	global_load_dword v166, v[106:107], off offset:12
	v_readlane_b32 s16, v254, 16
	s_waitcnt vmcnt(1)
	v_lshlrev_b64 v[100:101], 12, v[148:149]
	v_lshlrev_b32_e32 v116, 2, v160
	v_readlane_b32 s17, v254, 17
	v_ashrrev_i32_e32 v117, 31, v116
	s_mov_b32 s69, s65
	v_lshl_add_u64 v[100:101], s[16:17], 0, v[100:101]
	v_lshl_add_u64 v[100:101], v[116:117], 2, v[100:101]
	v_lshl_add_u64 v[114:115], v[100:101], 0, s[68:69]
	s_mov_b32 s71, s65
	v_lshl_add_u64 v[112:113], v[100:101], 0, s[70:71]
	s_mov_b32 s73, s65
	v_lshl_add_u64 v[110:111], v[100:101], 0, s[72:73]
	s_mov_b32 s67, s65
	s_ashr_i32 s46, s24, 6
	v_lshl_add_u64 v[108:109], v[100:101], 0, s[66:67]
	s_add_i32 s48, s46, -1
	v_cmp_gt_u32_e32 vcc, 16, v158
	s_waitcnt vmcnt(3)
	v_pk_mul_f32 v[96:97], v[96:97], v[98:99] op_sel_hi:[1,0]
	v_pk_mul_f32 v[94:95], v[94:95], v[98:99] op_sel_hi:[1,0]
	v_pk_mul_f32 v[92:93], v[92:93], v[98:99] op_sel_hi:[1,0]
	v_pk_mul_f32 v[90:91], v[90:91], v[98:99] op_sel_hi:[1,0]
	v_pk_mul_f32 v[88:89], v[88:89], v[98:99] op_sel_hi:[1,0]
	v_pk_mul_f32 v[86:87], v[86:87], v[98:99] op_sel_hi:[1,0]
	v_pk_mul_f32 v[84:85], v[84:85], v[98:99] op_sel_hi:[1,0]
	v_pk_mul_f32 v[82:83], v[82:83], v[98:99] op_sel_hi:[1,0]
	global_store_dwordx4 v[114:115], v[94:97], off
	global_store_dwordx4 v[114:115], v[90:93], off offset:64
	global_store_dwordx4 v[114:115], v[86:89], off offset:128
	global_store_dwordx4 v[114:115], v[82:85], off offset:192
	s_waitcnt vmcnt(6)
	v_pk_mul_f32 v[80:81], v[80:81], v[162:163] op_sel_hi:[1,0]
	v_pk_mul_f32 v[78:79], v[78:79], v[162:163] op_sel_hi:[1,0]
	v_pk_mul_f32 v[76:77], v[76:77], v[162:163] op_sel_hi:[1,0]
	v_pk_mul_f32 v[74:75], v[74:75], v[162:163] op_sel_hi:[1,0]
	v_pk_mul_f32 v[72:73], v[72:73], v[162:163] op_sel_hi:[1,0]
	v_pk_mul_f32 v[70:71], v[70:71], v[162:163] op_sel_hi:[1,0]
	v_pk_mul_f32 v[68:69], v[68:69], v[162:163] op_sel_hi:[1,0]
	v_pk_mul_f32 v[66:67], v[66:67], v[162:163] op_sel_hi:[1,0]
	global_store_dwordx4 v[112:113], v[78:81], off
	global_store_dwordx4 v[112:113], v[74:77], off offset:64
	global_store_dwordx4 v[112:113], v[70:73], off offset:128
	global_store_dwordx4 v[112:113], v[66:69], off offset:192
	s_waitcnt vmcnt(9)
	v_pk_mul_f32 v[64:65], v[64:65], v[164:165] op_sel_hi:[1,0]
	v_pk_mul_f32 v[62:63], v[62:63], v[164:165] op_sel_hi:[1,0]
	v_pk_mul_f32 v[60:61], v[60:61], v[164:165] op_sel_hi:[1,0]
	v_pk_mul_f32 v[58:59], v[58:59], v[164:165] op_sel_hi:[1,0]
	v_pk_mul_f32 v[56:57], v[56:57], v[164:165] op_sel_hi:[1,0]
	v_pk_mul_f32 v[54:55], v[54:55], v[164:165] op_sel_hi:[1,0]
	v_pk_mul_f32 v[52:53], v[52:53], v[164:165] op_sel_hi:[1,0]
	v_pk_mul_f32 v[50:51], v[50:51], v[164:165] op_sel_hi:[1,0]
	global_store_dwordx4 v[110:111], v[62:65], off
	global_store_dwordx4 v[110:111], v[58:61], off offset:64
	global_store_dwordx4 v[110:111], v[54:57], off offset:128
	global_store_dwordx4 v[110:111], v[50:53], off offset:192
	s_waitcnt vmcnt(12)
	v_pk_mul_f32 v[48:49], v[48:49], v[166:167] op_sel_hi:[1,0]
	v_pk_mul_f32 v[46:47], v[46:47], v[166:167] op_sel_hi:[1,0]
	v_lshlrev_b32_e32 v50, 5, v160
	v_pk_mul_f32 v[44:45], v[44:45], v[166:167] op_sel_hi:[1,0]
	v_pk_mul_f32 v[42:43], v[42:43], v[166:167] op_sel_hi:[1,0]
	v_pk_mul_f32 v[40:41], v[40:41], v[166:167] op_sel_hi:[1,0]
	v_pk_mul_f32 v[38:39], v[38:39], v[166:167] op_sel_hi:[1,0]
	v_pk_mul_f32 v[36:37], v[36:37], v[166:167] op_sel_hi:[1,0]
	v_pk_mul_f32 v[34:35], v[34:35], v[166:167] op_sel_hi:[1,0]
	global_store_dwordx4 v[108:109], v[46:49], off
	global_store_dwordx4 v[108:109], v[42:45], off offset:64
	global_store_dwordx4 v[108:109], v[38:41], off offset:128
	global_store_dwordx4 v[108:109], v[34:37], off offset:192
	s_waitcnt lgkmcnt(0)
	v_cmp_eq_u32_e64 s[16:17], s46, v50
	v_cmp_eq_u32_e64 s[18:19], s48, v50
	s_or_b64 s[16:17], s[16:17], s[18:19]
	v_add_u32_e32 v51, v1, v161
	s_nor_b64 s[16:17], vcc, s[16:17]
	s_and_saveexec_b64 s[18:19], s[16:17]
	s_xor_b64 s[18:19], exec, s[18:19]
	s_cbranch_execz .LBB0_2540
	v_lshl_add_u32 v1, v50, 2, v51
	ds_read_b32 v1, v1
	v_sub_u32_e32 v34, 0x7f, v50
	s_movk_i32 s16, 0xff80
	s_waitcnt lgkmcnt(0)
	v_and_or_b32 v1, v1, s16, v34
	v_add_u32_e32 v1, 0x80, v1
	v_cmp_ge_i32_e64 s[16:17], s46, v50
	s_nop 1
	v_cndmask_b32_e64 v37, 0, v1, s[16:17]

.LBB0_2698:
	v_mov_b32_e32 v1, v123
	s_nop 1
	v_permlane16_swap_b32 v123, v1
	v_mov_b32_e32 v53, v122
	v_add_f32_e32 v1, v123, v1
	v_mov_b32_e32 v50, v1
	s_nop 1
	v_permlane32_swap_b32 v50, v1
	global_load_dword v51, v[106:107], off offset:64
	global_load_dwordx4 v[34:37], v[114:115], off
	global_load_dwordx4 v[38:41], v[114:115], off offset:64
	global_load_dwordx4 v[42:45], v[114:115], off offset:128
	global_load_dwordx4 v[46:49], v[114:115], off offset:192
	global_load_dword v90, v[106:107], off offset:68
	global_load_dwordx4 v[58:61], v[112:113], off
	global_load_dwordx4 v[62:65], v[112:113], off offset:64
	global_load_dwordx4 v[66:69], v[112:113], off offset:128
	global_load_dwordx4 v[70:73], v[112:113], off offset:192
	global_load_dword v91, v[106:107], off offset:72
	global_load_dwordx4 v[74:77], v[110:111], off
	global_load_dwordx4 v[78:81], v[110:111], off offset:64
	global_load_dwordx4 v[82:85], v[110:111], off offset:128
	global_load_dwordx4 v[86:89], v[110:111], off offset:192
	global_load_dword v92, v[106:107], off offset:76
	global_load_dwordx4 v[236:239], v[108:109], off
	global_load_dwordx4 v[240:243], v[108:109], off offset:64
	global_load_dwordx4 v[244:247], v[108:109], off offset:128
	global_load_dwordx4 v[248:251], v[108:109], off offset:192
	v_add_f32_e32 v1, v50, v1
	v_max_f32_e32 v1, 0xda24260, v1
	s_waitcnt vmcnt(19)
	v_div_scale_f32 v50, s[16:17], v1, v1, v51
	v_rcp_f32_e32 v52, v50
	v_div_scale_f32 v54, vcc, v51, v1, v51
	v_fma_f32 v55, -v50, v52, 1.0
	v_fmac_f32_e32 v52, v55, v52
	v_mul_f32_e32 v55, v54, v52
	v_fma_f32 v56, -v50, v55, v54
	v_fmac_f32_e32 v55, v56, v52
	v_fma_f32 v50, -v50, v55, v54
	v_div_fmas_f32 v50, v50, v52, v55
	v_div_fixup_f32 v50, v50, v1, v51
	s_waitcnt vmcnt(18)
	v_pk_fma_f32 v[36:37], v[198:199], v[50:51], v[36:37] op_sel_hi:[1,0,1]
	v_pk_fma_f32 v[34:35], v[200:201], v[50:51], v[34:35] op_sel_hi:[1,0,1]
	s_waitcnt vmcnt(17)
	v_pk_fma_f32 v[40:41], v[202:203], v[50:51], v[40:41] op_sel_hi:[1,0,1]
	v_pk_fma_f32 v[38:39], v[204:205], v[50:51], v[38:39] op_sel_hi:[1,0,1]
	s_waitcnt vmcnt(16)
	v_pk_fma_f32 v[44:45], v[206:207], v[50:51], v[44:45] op_sel_hi:[1,0,1]
	v_pk_fma_f32 v[42:43], v[208:209], v[50:51], v[42:43] op_sel_hi:[1,0,1]
	s_waitcnt vmcnt(15)
	v_pk_fma_f32 v[48:49], v[210:211], v[50:51], v[48:49] op_sel_hi:[1,0,1]
	v_pk_fma_f32 v[46:47], v[212:213], v[50:51], v[46:47] op_sel_hi:[1,0,1]
	global_store_dwordx4 v[114:115], v[34:37], off
	global_store_dwordx4 v[114:115], v[38:41], off offset:64
	global_store_dwordx4 v[114:115], v[42:45], off offset:128
	global_store_dwordx4 v[114:115], v[46:49], off offset:192
	s_nop 1
	v_permlane16_swap_b32 v122, v53
	s_nop 0
	v_add_f32_e32 v1, v122, v53
	v_mov_b32_e32 v50, v1
	s_nop 1
	v_permlane32_swap_b32 v50, v1
	v_add_f32_e32 v1, v50, v1
	v_max_f32_e32 v1, 0xda24260, v1
	v_mov_b32_e32 v53, v121
	s_waitcnt vmcnt(18)
	v_div_scale_f32 v50, s[16:17], v1, v1, v90
	v_rcp_f32_e32 v52, v50
	v_div_scale_f32 v54, vcc, v90, v1, v90
	v_fma_f32 v55, -v50, v52, 1.0
	v_fmac_f32_e32 v52, v55, v52
	v_mul_f32_e32 v55, v54, v52
	v_fma_f32 v56, -v50, v55, v54
	v_fmac_f32_e32 v55, v56, v52
	v_fma_f32 v50, -v50, v55, v54
	v_div_fmas_f32 v50, v50, v52, v55
	v_div_fixup_f32 v50, v50, v1, v90
	s_waitcnt vmcnt(17)
	v_pk_fma_f32 v[36:37], v[182:183], v[50:51], v[60:61] op_sel_hi:[1,0,1]
	v_pk_fma_f32 v[34:35], v[184:185], v[50:51], v[58:59] op_sel_hi:[1,0,1]
	s_waitcnt vmcnt(16)
	v_pk_fma_f32 v[40:41], v[186:187], v[50:51], v[64:65] op_sel_hi:[1,0,1]
	v_pk_fma_f32 v[38:39], v[188:189], v[50:51], v[62:63] op_sel_hi:[1,0,1]
	s_waitcnt vmcnt(15)
	v_pk_fma_f32 v[44:45], v[190:191], v[50:51], v[68:69] op_sel_hi:[1,0,1]
	v_pk_fma_f32 v[42:43], v[192:193], v[50:51], v[66:67] op_sel_hi:[1,0,1]
	s_waitcnt vmcnt(14)
	v_pk_fma_f32 v[48:49], v[194:195], v[50:51], v[72:73] op_sel_hi:[1,0,1]
	v_pk_fma_f32 v[46:47], v[196:197], v[50:51], v[70:71] op_sel_hi:[1,0,1]
	global_store_dwordx4 v[112:113], v[34:37], off
	global_store_dwordx4 v[112:113], v[38:41], off offset:64
	global_store_dwordx4 v[112:113], v[42:45], off offset:128
	global_store_dwordx4 v[112:113], v[46:49], off offset:192
	s_nop 1
	v_permlane16_swap_b32 v121, v53
	s_nop 0
	v_add_f32_e32 v1, v121, v53
	v_mov_b32_e32 v50, v1
	s_nop 1
	v_permlane32_swap_b32 v1, v50
	v_add_f32_e32 v1, v1, v50
	v_max_f32_e32 v1, 0xda24260, v1
	v_mov_b32_e32 v53, v120
	s_waitcnt vmcnt(17)
	v_div_scale_f32 v50, s[16:17], v1, v1, v91
	v_rcp_f32_e32 v52, v50
	v_div_scale_f32 v54, vcc, v91, v1, v91
	s_max_i32 s17, s27, 0x1ff
	v_fma_f32 v55, -v50, v52, 1.0
	v_fmac_f32_e32 v52, v55, v52
	v_mul_f32_e32 v55, v54, v52
	v_fma_f32 v56, -v50, v55, v54
	v_fmac_f32_e32 v55, v56, v52
	v_fma_f32 v50, -v50, v55, v54
	v_div_fmas_f32 v50, v50, v52, v55
	v_div_fixup_f32 v50, v50, v1, v91
	s_waitcnt vmcnt(16)
	v_pk_fma_f32 v[36:37], v[176:177], v[50:51], v[76:77] op_sel_hi:[1,0,1]
	v_pk_fma_f32 v[34:35], v[178:179], v[50:51], v[74:75] op_sel_hi:[1,0,1]
	s_waitcnt vmcnt(15)
	v_pk_fma_f32 v[40:41], v[172:173], v[50:51], v[80:81] op_sel_hi:[1,0,1]
	v_pk_fma_f32 v[38:39], v[174:175], v[50:51], v[78:79] op_sel_hi:[1,0,1]
	s_waitcnt vmcnt(14)
	v_pk_fma_f32 v[44:45], v[168:169], v[50:51], v[84:85] op_sel_hi:[1,0,1]
	v_pk_fma_f32 v[42:43], v[170:171], v[50:51], v[82:83] op_sel_hi:[1,0,1]
	s_waitcnt vmcnt(13)
	v_pk_fma_f32 v[48:49], v[164:165], v[50:51], v[88:89] op_sel_hi:[1,0,1]
	v_pk_fma_f32 v[46:47], v[166:167], v[50:51], v[86:87] op_sel_hi:[1,0,1]
	global_store_dwordx4 v[110:111], v[34:37], off
	global_store_dwordx4 v[110:111], v[38:41], off offset:64
	global_store_dwordx4 v[110:111], v[42:45], off offset:128
	global_store_dwordx4 v[110:111], v[46:49], off offset:192
	s_nop 1
	v_permlane16_swap_b32 v120, v53
	s_lshl_b32 s16, s25, 1
	v_add_f32_e32 v1, v120, v53
	v_mov_b32_e32 v50, v1
	s_nop 1
	v_permlane32_swap_b32 v50, v1
	s_addk_i32 s17, 0xfe01
	v_add_f32_e32 v1, v50, v1
	s_or_b32 s18, s16, 1
	s_lshr_b32 s25, s17, 6
	v_max_f32_e32 v1, 0xda24260, v1
	s_sub_i32 s27, s18, s25
	s_cmp_gt_i32 s27, -1
	s_waitcnt vmcnt(16)
	v_div_scale_f32 v50, s[18:19], v1, v1, v92
	v_rcp_f32_e32 v52, v50
	v_div_scale_f32 v53, vcc, v92, v1, v92
	v_fma_f32 v54, -v50, v52, 1.0
	v_fmac_f32_e32 v52, v54, v52
	v_mul_f32_e32 v54, v53, v52
	v_fma_f32 v55, -v50, v54, v53
	v_fmac_f32_e32 v54, v55, v52
	v_fma_f32 v50, -v50, v54, v53
	v_div_fmas_f32 v50, v50, v52, v54
	v_div_fixup_f32 v50, v50, v1, v92
	s_waitcnt vmcnt(15)
	v_pk_fma_f32 v[36:37], v[160:161], v[50:51], v[238:239] op_sel_hi:[1,0,1]
	v_pk_fma_f32 v[34:35], v[162:163], v[50:51], v[236:237] op_sel_hi:[1,0,1]
	s_waitcnt vmcnt(14)
	v_pk_fma_f32 v[40:41], v[156:157], v[50:51], v[242:243] op_sel_hi:[1,0,1]
	v_pk_fma_f32 v[38:39], v[158:159], v[50:51], v[240:241] op_sel_hi:[1,0,1]
	s_waitcnt vmcnt(13)
	v_pk_fma_f32 v[44:45], v[152:153], v[50:51], v[246:247] op_sel_hi:[1,0,1]
	v_pk_fma_f32 v[42:43], v[154:155], v[50:51], v[244:245] op_sel_hi:[1,0,1]
	s_waitcnt vmcnt(12)
	v_pk_fma_f32 v[48:49], v[148:149], v[50:51], v[250:251] op_sel_hi:[1,0,1]
	v_pk_fma_f32 v[46:47], v[150:151], v[50:51], v[248:249] op_sel_hi:[1,0,1]
	global_store_dwordx4 v[108:109], v[34:37], off
	global_store_dwordx4 v[108:109], v[38:41], off offset:64
	global_store_dwordx4 v[108:109], v[42:45], off offset:128
	global_store_dwordx4 v[108:109], v[46:49], off offset:192
	s_cbranch_scc0 .LBB0_2700
	s_and_b32 s18, s17, 0xffffffc0
	v_or_b32_e32 v34, s18, v214
	v_mov_b32_e32 v35, 0
	v_lshlrev_b64 v[36:37], 7, v[34:35]
	s_mov_b32 s19, 0
	v_lshl_add_u64 v[36:37], s[22:23], 0, v[36:37]
	v_mov_b32_e32 v131, v35
	v_lshl_add_u64 v[34:35], v[36:37], 0, v[130:131]
	v_lshl_add_u64 v[36:37], s[18:19], 1, v[132:133]
	v_lshl_add_u64 v[38:39], v[36:37], 0, v[130:131]
	global_load_dwordx4 v[34:37], v[34:35], off
	s_nop 0
	global_load_dwordx4 v[38:41], v[38:39], off
	s_mov_b32 s17, 0x12c00
	v_add3_u32 v1, v229, v220, s17
	s_waitcnt vmcnt(1)
	ds_write_b128 v228, v[34:37]
	s_waitcnt vmcnt(0)
	ds_write_b128 v1, v[38:41]

.LBB0_2714:
	global_load_dword v98, v[106:107], off offset:128
	global_load_dword v99, v[106:107], off offset:132
	global_load_dword v100, v[106:107], off offset:136
	global_load_dword v101, v[106:107], off offset:140
	global_load_dwordx4 v[164:167], v[114:115], off
	global_load_dwordx4 v[168:171], v[114:115], off offset:64
	global_load_dwordx4 v[172:175], v[114:115], off offset:128
	global_load_dwordx4 v[176:179], v[114:115], off offset:192
	global_load_dwordx4 v[180:183], v[112:113], off
	global_load_dwordx4 v[184:187], v[112:113], off offset:64
	global_load_dwordx4 v[188:191], v[112:113], off offset:128
	global_load_dwordx4 v[192:195], v[112:113], off offset:192
	global_load_dwordx4 v[196:199], v[110:111], off
	global_load_dwordx4 v[200:203], v[110:111], off offset:64
	global_load_dwordx4 v[204:207], v[110:111], off offset:128
	global_load_dwordx4 v[208:211], v[110:111], off offset:192
	global_load_dwordx4 v[228:231], v[108:109], off
	global_load_dwordx4 v[232:235], v[108:109], off offset:64
	global_load_dwordx4 v[236:239], v[108:109], off offset:128
	global_load_dwordx4 v[240:243], v[108:109], off offset:192
	v_mov_b32_e32 v1, v2
	s_nop 1
	v_permlane16_swap_b32 v2, v1
	v_readlane_b32 s16, v254, 12
	v_add_f32_e32 v1, v2, v1
	v_mov_b32_e32 v8, v1
	s_nop 1
	v_permlane32_swap_b32 v8, v1
	v_add_f32_e32 v1, v8, v1
	v_readlane_b32 s17, v254, 13
	v_max_f32_e32 v1, 0xda24260, v1
	s_mov_b32 s57, 0
	v_lshl_add_u64 v[2:3], v[118:119], 1, s[16:17]
	v_lshl_add_u64 v[2:3], v[116:117], 1, v[2:3]
	v_lshl_add_u64 v[8:9], v[2:3], 0, s[56:57]
	s_mov_b32 s63, s57
	s_mov_b32 s61, s57
	s_mov_b32 s59, s57
	s_waitcnt vmcnt(16)
	v_div_scale_f32 v11, s[16:17], v1, v1, v98
	v_rcp_f32_e32 v12, v11
	v_div_scale_f32 v13, vcc, v98, v1, v98
	v_fma_f32 v14, -v11, v12, 1.0
	v_fmac_f32_e32 v12, v14, v12
	v_mul_f32_e32 v14, v13, v12
	v_fma_f32 v15, -v11, v14, v13
	v_fmac_f32_e32 v14, v15, v12
	v_fma_f32 v11, -v11, v14, v13
	v_div_fmas_f32 v11, v11, v12, v14
	v_div_fixup_f32 v10, v11, v1, v98
	s_waitcnt vmcnt(15)
	v_pk_fma_f32 v[6:7], v[96:97], v[10:11], v[166:167] op_sel_hi:[1,0,1]
	v_pk_fma_f32 v[4:5], v[94:95], v[10:11], v[164:165] op_sel_hi:[1,0,1]
	v_mov_b32_e32 v1, v122
	v_cvt_pk_bf16_f32 v4, v4, v5
	v_cvt_pk_bf16_f32 v5, v6, v7
	global_store_dwordx2 v[8:9], v[4:5], off
	s_waitcnt vmcnt(15)
	v_pk_fma_f32 v[6:7], v[92:93], v[10:11], v[170:171] op_sel_hi:[1,0,1]
	v_pk_fma_f32 v[4:5], v[90:91], v[10:11], v[168:169] op_sel_hi:[1,0,1]
	s_nop 0
	v_cvt_pk_bf16_f32 v4, v4, v5
	v_cvt_pk_bf16_f32 v5, v6, v7
	global_store_dwordx2 v[8:9], v[4:5], off offset:32
	s_waitcnt vmcnt(15)
	v_pk_fma_f32 v[6:7], v[88:89], v[10:11], v[174:175] op_sel_hi:[1,0,1]
	v_pk_fma_f32 v[4:5], v[86:87], v[10:11], v[172:173] op_sel_hi:[1,0,1]
	s_nop 0
	v_cvt_pk_bf16_f32 v4, v4, v5
	v_cvt_pk_bf16_f32 v5, v6, v7
	global_store_dwordx2 v[8:9], v[4:5], off offset:64
	s_waitcnt vmcnt(15)
	v_pk_fma_f32 v[6:7], v[84:85], v[10:11], v[178:179] op_sel_hi:[1,0,1]
	v_pk_fma_f32 v[4:5], v[82:83], v[10:11], v[176:177] op_sel_hi:[1,0,1]
	s_nop 0
	v_cvt_pk_bf16_f32 v4, v4, v5
	v_cvt_pk_bf16_f32 v5, v6, v7
	global_store_dwordx2 v[8:9], v[4:5], off offset:96
	s_nop 1
	v_permlane16_swap_b32 v122, v1
	s_nop 0
	v_add_f32_e32 v1, v122, v1
	v_mov_b32_e32 v8, v1
	s_nop 1
	v_permlane32_swap_b32 v1, v8
	v_add_f32_e32 v1, v1, v8
	v_max_f32_e32 v1, 0xda24260, v1
	v_lshl_add_u64 v[8:9], v[2:3], 0, s[62:63]
	s_waitcnt vmcnt(16)
	v_div_scale_f32 v11, s[16:17], v1, v1, v99
	v_rcp_f32_e32 v12, v11
	v_div_scale_f32 v13, vcc, v99, v1, v99
	v_fma_f32 v14, -v11, v12, 1.0
	v_fmac_f32_e32 v12, v14, v12
	v_mul_f32_e32 v14, v13, v12
	v_fma_f32 v15, -v11, v14, v13
	v_fmac_f32_e32 v14, v15, v12
	v_fma_f32 v11, -v11, v14, v13
	v_div_fmas_f32 v11, v11, v12, v14
	v_div_fixup_f32 v10, v11, v1, v99
	s_waitcnt vmcnt(15)
	v_pk_fma_f32 v[6:7], v[80:81], v[10:11], v[182:183] op_sel_hi:[1,0,1]
	v_pk_fma_f32 v[4:5], v[78:79], v[10:11], v[180:181] op_sel_hi:[1,0,1]
	v_mov_b32_e32 v1, v121
	v_cvt_pk_bf16_f32 v4, v4, v5
	v_cvt_pk_bf16_f32 v5, v6, v7
	global_store_dwordx2 v[8:9], v[4:5], off
	s_waitcnt vmcnt(15)
	v_pk_fma_f32 v[6:7], v[76:77], v[10:11], v[186:187] op_sel_hi:[1,0,1]
	v_pk_fma_f32 v[4:5], v[74:75], v[10:11], v[184:185] op_sel_hi:[1,0,1]
	s_nop 0
	v_cvt_pk_bf16_f32 v4, v4, v5
	v_cvt_pk_bf16_f32 v5, v6, v7
	global_store_dwordx2 v[8:9], v[4:5], off offset:32
	s_waitcnt vmcnt(15)
	v_pk_fma_f32 v[6:7], v[72:73], v[10:11], v[190:191] op_sel_hi:[1,0,1]
	v_pk_fma_f32 v[4:5], v[70:71], v[10:11], v[188:189] op_sel_hi:[1,0,1]
	s_nop 0
	v_cvt_pk_bf16_f32 v4, v4, v5
	v_cvt_pk_bf16_f32 v5, v6, v7
	global_store_dwordx2 v[8:9], v[4:5], off offset:64
	s_waitcnt vmcnt(15)
	v_pk_fma_f32 v[6:7], v[68:69], v[10:11], v[194:195] op_sel_hi:[1,0,1]
	v_pk_fma_f32 v[4:5], v[66:67], v[10:11], v[192:193] op_sel_hi:[1,0,1]
	s_nop 0
	v_cvt_pk_bf16_f32 v4, v4, v5
	v_cvt_pk_bf16_f32 v5, v6, v7
	global_store_dwordx2 v[8:9], v[4:5], off offset:96
	s_nop 1
	v_permlane16_swap_b32 v121, v1
	s_nop 0
	v_add_f32_e32 v1, v121, v1
	v_mov_b32_e32 v8, v1
	s_nop 1
	v_permlane32_swap_b32 v8, v1
	v_add_f32_e32 v1, v8, v1
	v_max_f32_e32 v1, 0xda24260, v1
	v_lshl_add_u64 v[8:9], v[2:3], 0, s[60:61]
	s_waitcnt vmcnt(16)
	v_div_scale_f32 v11, s[16:17], v1, v1, v100
	v_rcp_f32_e32 v12, v11
	v_div_scale_f32 v13, vcc, v100, v1, v100
	v_fma_f32 v14, -v11, v12, 1.0
	v_fmac_f32_e32 v12, v14, v12
	v_mul_f32_e32 v14, v13, v12
	v_fma_f32 v15, -v11, v14, v13
	v_fmac_f32_e32 v14, v15, v12
	v_fma_f32 v11, -v11, v14, v13
	v_div_fmas_f32 v11, v11, v12, v14
	v_div_fixup_f32 v10, v11, v1, v100
	s_waitcnt vmcnt(15)
	v_pk_fma_f32 v[6:7], v[64:65], v[10:11], v[198:199] op_sel_hi:[1,0,1]
	v_pk_fma_f32 v[4:5], v[62:63], v[10:11], v[196:197] op_sel_hi:[1,0,1]
	v_mov_b32_e32 v1, v120
	v_cvt_pk_bf16_f32 v4, v4, v5
	v_cvt_pk_bf16_f32 v5, v6, v7
	global_store_dwordx2 v[8:9], v[4:5], off
	s_waitcnt vmcnt(15)
	v_pk_fma_f32 v[6:7], v[60:61], v[10:11], v[202:203] op_sel_hi:[1,0,1]
	v_pk_fma_f32 v[4:5], v[58:59], v[10:11], v[200:201] op_sel_hi:[1,0,1]
	s_nop 0
	v_cvt_pk_bf16_f32 v4, v4, v5
	v_cvt_pk_bf16_f32 v5, v6, v7
	global_store_dwordx2 v[8:9], v[4:5], off offset:32
	s_waitcnt vmcnt(15)
	v_pk_fma_f32 v[6:7], v[56:57], v[10:11], v[206:207] op_sel_hi:[1,0,1]
	v_pk_fma_f32 v[4:5], v[54:55], v[10:11], v[204:205] op_sel_hi:[1,0,1]
	s_nop 0
	v_cvt_pk_bf16_f32 v4, v4, v5
	v_cvt_pk_bf16_f32 v5, v6, v7
	global_store_dwordx2 v[8:9], v[4:5], off offset:64
	s_waitcnt vmcnt(15)
	v_pk_fma_f32 v[6:7], v[52:53], v[10:11], v[210:211] op_sel_hi:[1,0,1]
	v_pk_fma_f32 v[4:5], v[50:51], v[10:11], v[208:209] op_sel_hi:[1,0,1]
	s_nop 0
	v_cvt_pk_bf16_f32 v4, v4, v5
	v_cvt_pk_bf16_f32 v5, v6, v7
	global_store_dwordx2 v[8:9], v[4:5], off offset:96
	s_nop 1
	v_permlane16_swap_b32 v120, v1
	s_nop 0
	v_add_f32_e32 v1, v120, v1
	v_mov_b32_e32 v8, v1
	s_nop 1
	v_permlane32_swap_b32 v8, v1
	v_add_f32_e32 v1, v8, v1
	v_max_f32_e32 v1, 0xda24260, v1
	v_lshl_add_u64 v[8:9], v[2:3], 0, s[58:59]
	s_waitcnt vmcnt(16)
	v_div_scale_f32 v11, s[16:17], v1, v1, v101
	v_rcp_f32_e32 v12, v11
	v_div_scale_f32 v2, vcc, v101, v1, v101
	s_mov_b64 s[16:17], 0
	v_fma_f32 v3, -v11, v12, 1.0
	v_fmac_f32_e32 v12, v3, v12
	v_mul_f32_e32 v3, v2, v12
	v_fma_f32 v13, -v11, v3, v2
	v_fmac_f32_e32 v3, v13, v12
	v_fma_f32 v2, -v11, v3, v2
	v_div_fmas_f32 v2, v2, v12, v3
	v_div_fixup_f32 v10, v2, v1, v101
	s_waitcnt vmcnt(15)
	v_pk_fma_f32 v[2:3], v[48:49], v[10:11], v[230:231] op_sel_hi:[1,0,1]
	v_pk_fma_f32 v[4:5], v[46:47], v[10:11], v[228:229] op_sel_hi:[1,0,1]
	s_nop 0
	v_cvt_pk_bf16_f32 v4, v4, v5
	v_cvt_pk_bf16_f32 v5, v2, v3
	global_store_dwordx2 v[8:9], v[4:5], off
	s_waitcnt vmcnt(15)
	v_pk_fma_f32 v[4:5], v[44:45], v[10:11], v[234:235] op_sel_hi:[1,0,1]
	v_pk_fma_f32 v[2:3], v[42:43], v[10:11], v[232:233] op_sel_hi:[1,0,1]
	s_nop 0
	v_cvt_pk_bf16_f32 v2, v2, v3
	v_cvt_pk_bf16_f32 v3, v4, v5
	global_store_dwordx2 v[8:9], v[2:3], off offset:32
	s_waitcnt vmcnt(15)
	v_pk_fma_f32 v[4:5], v[40:41], v[10:11], v[238:239] op_sel_hi:[1,0,1]
	v_pk_fma_f32 v[2:3], v[38:39], v[10:11], v[236:237] op_sel_hi:[1,0,1]
	s_nop 0
	v_cvt_pk_bf16_f32 v2, v2, v3
	v_cvt_pk_bf16_f32 v3, v4, v5
	global_store_dwordx2 v[8:9], v[2:3], off offset:64
	s_waitcnt vmcnt(15)
	v_pk_fma_f32 v[4:5], v[36:37], v[10:11], v[242:243] op_sel_hi:[1,0,1]
	v_pk_fma_f32 v[2:3], v[34:35], v[10:11], v[240:241] op_sel_hi:[1,0,1]
	s_nop 0
	v_cvt_pk_bf16_f32 v2, v2, v3
	v_cvt_pk_bf16_f32 v3, v4, v5
	global_store_dwordx2 v[8:9], v[2:3], off offset:96
	s_barrier

.LBB0_2752:
	v_readlane_b32 s18, v254, 14
	v_readlane_b32 s19, v254, 15
	s_movk_i32 s16, 0xc0
	s_lshl_b32 s64, s47, 2
	v_mov_b64_e32 v[98:99], s[18:19]
	v_mad_i64_i32 v[98:99], s[16:17], v148, s16, v[98:99]
	s_mov_b32 s65, 0
	s_waitcnt vmcnt(1)
	v_lshl_add_u64 v[106:107], v[98:99], 0, s[64:65]
	global_load_dword v98, v[106:107], off
	global_load_dword v162, v[106:107], off offset:4
	global_load_dword v164, v[106:107], off offset:8
	global_load_dword v166, v[106:107], off offset:12
	v_readlane_b32 s16, v254, 16
	s_waitcnt vmcnt(1)
	v_lshlrev_b64 v[100:101], 12, v[148:149]
	v_lshlrev_b32_e32 v116, 2, v160
	v_readlane_b32 s17, v254, 17
	v_ashrrev_i32_e32 v117, 31, v116
	s_lshl_b32 s68, s45, 2
	v_lshl_add_u64 v[100:101], s[16:17], 0, v[100:101]
	s_mov_b32 s69, s65
	v_lshl_add_u64 v[100:101], v[116:117], 2, v[100:101]
	v_lshl_add_u64 v[114:115], v[100:101], 0, s[68:69]
	s_lshl_b32 s70, s43, 2
	s_mov_b32 s71, s65
	v_lshl_add_u64 v[112:113], v[100:101], 0, s[70:71]
	s_lshl_b32 s72, s42, 2
	s_mov_b32 s73, s65
	v_lshl_add_u64 v[110:111], v[100:101], 0, s[72:73]
	s_lshl_b32 s66, s41, 2
	s_mov_b32 s67, s65
	s_ashr_i32 s27, s24, 6
	v_lshl_add_u64 v[108:109], v[100:101], 0, s[66:67]
	s_add_i32 s41, s27, -1
	v_cmp_gt_u32_e32 vcc, 16, v158
	s_waitcnt vmcnt(3)
	v_pk_mul_f32 v[96:97], v[96:97], v[98:99] op_sel_hi:[1,0]
	v_pk_mul_f32 v[94:95], v[94:95], v[98:99] op_sel_hi:[1,0]
	v_pk_mul_f32 v[92:93], v[92:93], v[98:99] op_sel_hi:[1,0]
	v_pk_mul_f32 v[90:91], v[90:91], v[98:99] op_sel_hi:[1,0]
	v_pk_mul_f32 v[88:89], v[88:89], v[98:99] op_sel_hi:[1,0]
	v_pk_mul_f32 v[86:87], v[86:87], v[98:99] op_sel_hi:[1,0]
	v_pk_mul_f32 v[84:85], v[84:85], v[98:99] op_sel_hi:[1,0]
	v_pk_mul_f32 v[82:83], v[82:83], v[98:99] op_sel_hi:[1,0]
	global_store_dwordx4 v[114:115], v[94:97], off
	global_store_dwordx4 v[114:115], v[90:93], off offset:64
	global_store_dwordx4 v[114:115], v[86:89], off offset:128
	global_store_dwordx4 v[114:115], v[82:85], off offset:192
	s_waitcnt vmcnt(6)
	v_pk_mul_f32 v[80:81], v[80:81], v[162:163] op_sel_hi:[1,0]
	v_pk_mul_f32 v[78:79], v[78:79], v[162:163] op_sel_hi:[1,0]
	v_pk_mul_f32 v[76:77], v[76:77], v[162:163] op_sel_hi:[1,0]
	v_pk_mul_f32 v[74:75], v[74:75], v[162:163] op_sel_hi:[1,0]
	v_pk_mul_f32 v[72:73], v[72:73], v[162:163] op_sel_hi:[1,0]
	v_pk_mul_f32 v[70:71], v[70:71], v[162:163] op_sel_hi:[1,0]
	v_pk_mul_f32 v[68:69], v[68:69], v[162:163] op_sel_hi:[1,0]
	v_pk_mul_f32 v[66:67], v[66:67], v[162:163] op_sel_hi:[1,0]
	global_store_dwordx4 v[112:113], v[78:81], off
	global_store_dwordx4 v[112:113], v[74:77], off offset:64
	global_store_dwordx4 v[112:113], v[70:73], off offset:128
	global_store_dwordx4 v[112:113], v[66:69], off offset:192
	s_waitcnt vmcnt(9)
	v_pk_mul_f32 v[64:65], v[64:65], v[164:165] op_sel_hi:[1,0]
	v_pk_mul_f32 v[62:63], v[62:63], v[164:165] op_sel_hi:[1,0]
	v_pk_mul_f32 v[60:61], v[60:61], v[164:165] op_sel_hi:[1,0]
	v_pk_mul_f32 v[58:59], v[58:59], v[164:165] op_sel_hi:[1,0]
	v_pk_mul_f32 v[56:57], v[56:57], v[164:165] op_sel_hi:[1,0]
	v_pk_mul_f32 v[54:55], v[54:55], v[164:165] op_sel_hi:[1,0]
	v_pk_mul_f32 v[52:53], v[52:53], v[164:165] op_sel_hi:[1,0]
	v_pk_mul_f32 v[50:51], v[50:51], v[164:165] op_sel_hi:[1,0]
	global_store_dwordx4 v[110:111], v[62:65], off
	global_store_dwordx4 v[110:111], v[58:61], off offset:64
	global_store_dwordx4 v[110:111], v[54:57], off offset:128
	global_store_dwordx4 v[110:111], v[50:53], off offset:192
	s_waitcnt vmcnt(12)
	v_pk_mul_f32 v[48:49], v[48:49], v[166:167] op_sel_hi:[1,0]
	v_pk_mul_f32 v[46:47], v[46:47], v[166:167] op_sel_hi:[1,0]
	v_lshlrev_b32_e32 v50, 5, v160
	v_pk_mul_f32 v[44:45], v[44:45], v[166:167] op_sel_hi:[1,0]
	v_pk_mul_f32 v[42:43], v[42:43], v[166:167] op_sel_hi:[1,0]
	v_pk_mul_f32 v[40:41], v[40:41], v[166:167] op_sel_hi:[1,0]
	v_pk_mul_f32 v[38:39], v[38:39], v[166:167] op_sel_hi:[1,0]
	v_pk_mul_f32 v[36:37], v[36:37], v[166:167] op_sel_hi:[1,0]
	v_pk_mul_f32 v[34:35], v[34:35], v[166:167] op_sel_hi:[1,0]
	global_store_dwordx4 v[108:109], v[46:49], off
	global_store_dwordx4 v[108:109], v[42:45], off offset:64
	global_store_dwordx4 v[108:109], v[38:41], off offset:128
	global_store_dwordx4 v[108:109], v[34:37], off offset:192
	s_waitcnt lgkmcnt(0)
	v_cmp_eq_u32_e64 s[16:17], s27, v50
	v_cmp_eq_u32_e64 s[18:19], s41, v50
	s_or_b64 s[16:17], s[16:17], s[18:19]
	v_add_u32_e32 v51, v1, v125
	s_nor_b64 s[16:17], vcc, s[16:17]
	s_and_saveexec_b64 s[18:19], s[16:17]
	s_xor_b64 s[18:19], exec, s[18:19]
	s_cbranch_execz .LBB0_2754
	v_lshl_add_u32 v1, v50, 2, v51
	ds_read_b32 v1, v1
	v_sub_u32_e32 v34, 0x7f, v50
	s_movk_i32 s16, 0xff80
	s_waitcnt lgkmcnt(0)
	v_and_or_b32 v1, v1, s16, v34
	v_add_u32_e32 v1, 0x80, v1
	v_cmp_ge_i32_e64 s[16:17], s27, v50
	s_nop 1
	v_cndmask_b32_e64 v37, 0, v1, s[16:17]

.LBB0_2912:
	v_mov_b32_e32 v1, v123
	s_nop 1
	v_permlane16_swap_b32 v123, v1
	v_mov_b32_e32 v53, v122
	v_add_f32_e32 v1, v123, v1
	v_mov_b32_e32 v50, v1
	s_nop 1
	v_permlane32_swap_b32 v1, v50
	global_load_dword v51, v[106:107], off offset:64
	global_load_dwordx4 v[34:37], v[114:115], off
	global_load_dwordx4 v[38:41], v[114:115], off offset:64
	global_load_dwordx4 v[42:45], v[114:115], off offset:128
	global_load_dwordx4 v[46:49], v[114:115], off offset:192
	global_load_dword v90, v[106:107], off offset:68
	global_load_dwordx4 v[58:61], v[112:113], off
	global_load_dwordx4 v[62:65], v[112:113], off offset:64
	global_load_dwordx4 v[66:69], v[112:113], off offset:128
	global_load_dwordx4 v[70:73], v[112:113], off offset:192
	global_load_dword v91, v[106:107], off offset:72
	global_load_dwordx4 v[74:77], v[110:111], off
	global_load_dwordx4 v[78:81], v[110:111], off offset:64
	global_load_dwordx4 v[82:85], v[110:111], off offset:128
	global_load_dwordx4 v[86:89], v[110:111], off offset:192
	global_load_dword v92, v[106:107], off offset:76
	global_load_dwordx4 v[236:239], v[108:109], off
	global_load_dwordx4 v[240:243], v[108:109], off offset:64
	global_load_dwordx4 v[244:247], v[108:109], off offset:128
	global_load_dwordx4 v[248:251], v[108:109], off offset:192
	v_add_f32_e32 v1, v1, v50
	v_max_f32_e32 v1, 0xda24260, v1
	s_waitcnt vmcnt(19)
	v_div_scale_f32 v50, s[16:17], v1, v1, v51
	v_rcp_f32_e32 v52, v50
	v_div_scale_f32 v54, vcc, v51, v1, v51
	v_fma_f32 v55, -v50, v52, 1.0
	v_fmac_f32_e32 v52, v55, v52
	v_mul_f32_e32 v55, v54, v52
	v_fma_f32 v56, -v50, v55, v54
	v_fmac_f32_e32 v55, v56, v52
	v_fma_f32 v50, -v50, v55, v54
	v_div_fmas_f32 v50, v50, v52, v55
	v_div_fixup_f32 v50, v50, v1, v51
	s_waitcnt vmcnt(18)
	v_pk_fma_f32 v[36:37], v[198:199], v[50:51], v[36:37] op_sel_hi:[1,0,1]
	v_pk_fma_f32 v[34:35], v[200:201], v[50:51], v[34:35] op_sel_hi:[1,0,1]
	s_waitcnt vmcnt(17)
	v_pk_fma_f32 v[40:41], v[202:203], v[50:51], v[40:41] op_sel_hi:[1,0,1]
	v_pk_fma_f32 v[38:39], v[204:205], v[50:51], v[38:39] op_sel_hi:[1,0,1]
	s_waitcnt vmcnt(16)
	v_pk_fma_f32 v[44:45], v[206:207], v[50:51], v[44:45] op_sel_hi:[1,0,1]
	v_pk_fma_f32 v[42:43], v[208:209], v[50:51], v[42:43] op_sel_hi:[1,0,1]
	s_waitcnt vmcnt(15)
	v_pk_fma_f32 v[48:49], v[210:211], v[50:51], v[48:49] op_sel_hi:[1,0,1]
	v_pk_fma_f32 v[46:47], v[212:213], v[50:51], v[46:47] op_sel_hi:[1,0,1]
	global_store_dwordx4 v[114:115], v[34:37], off
	global_store_dwordx4 v[114:115], v[38:41], off offset:64
	global_store_dwordx4 v[114:115], v[42:45], off offset:128
	global_store_dwordx4 v[114:115], v[46:49], off offset:192
	s_nop 1
	v_permlane16_swap_b32 v122, v53
	s_nop 0
	v_add_f32_e32 v1, v122, v53
	v_mov_b32_e32 v50, v1
	s_nop 1
	v_permlane32_swap_b32 v50, v1
	v_add_f32_e32 v1, v50, v1
	v_max_f32_e32 v1, 0xda24260, v1
	v_mov_b32_e32 v53, v121
	s_waitcnt vmcnt(18)
	v_div_scale_f32 v50, s[16:17], v1, v1, v90
	v_rcp_f32_e32 v52, v50
	v_div_scale_f32 v54, vcc, v90, v1, v90
	v_fma_f32 v55, -v50, v52, 1.0
	v_fmac_f32_e32 v52, v55, v52
	v_mul_f32_e32 v55, v54, v52
	v_fma_f32 v56, -v50, v55, v54
	v_fmac_f32_e32 v55, v56, v52
	v_fma_f32 v50, -v50, v55, v54
	v_div_fmas_f32 v50, v50, v52, v55
	v_div_fixup_f32 v50, v50, v1, v90
	s_waitcnt vmcnt(17)
	v_pk_fma_f32 v[36:37], v[182:183], v[50:51], v[60:61] op_sel_hi:[1,0,1]
	v_pk_fma_f32 v[34:35], v[184:185], v[50:51], v[58:59] op_sel_hi:[1,0,1]
	s_waitcnt vmcnt(16)
	v_pk_fma_f32 v[40:41], v[186:187], v[50:51], v[64:65] op_sel_hi:[1,0,1]
	v_pk_fma_f32 v[38:39], v[188:189], v[50:51], v[62:63] op_sel_hi:[1,0,1]
	s_waitcnt vmcnt(15)
	v_pk_fma_f32 v[44:45], v[190:191], v[50:51], v[68:69] op_sel_hi:[1,0,1]
	v_pk_fma_f32 v[42:43], v[192:193], v[50:51], v[66:67] op_sel_hi:[1,0,1]
	s_waitcnt vmcnt(14)
	v_pk_fma_f32 v[48:49], v[194:195], v[50:51], v[72:73] op_sel_hi:[1,0,1]
	v_pk_fma_f32 v[46:47], v[196:197], v[50:51], v[70:71] op_sel_hi:[1,0,1]
	global_store_dwordx4 v[112:113], v[34:37], off
	global_store_dwordx4 v[112:113], v[38:41], off offset:64
	global_store_dwordx4 v[112:113], v[42:45], off offset:128
	global_store_dwordx4 v[112:113], v[46:49], off offset:192
	s_nop 1
	v_permlane16_swap_b32 v121, v53
	s_nop 0
	v_add_f32_e32 v1, v121, v53
	v_mov_b32_e32 v50, v1
	s_nop 1
	v_permlane32_swap_b32 v1, v50
	v_add_f32_e32 v1, v1, v50
	v_max_f32_e32 v1, 0xda24260, v1
	v_mov_b32_e32 v53, v120
	s_waitcnt vmcnt(17)
	v_div_scale_f32 v50, s[16:17], v1, v1, v91
	v_rcp_f32_e32 v52, v50
	v_div_scale_f32 v54, vcc, v91, v1, v91
	s_max_i32 s17, s25, 0x1ff
	v_fma_f32 v55, -v50, v52, 1.0
	v_fmac_f32_e32 v52, v55, v52
	v_mul_f32_e32 v55, v54, v52
	v_fma_f32 v56, -v50, v55, v54
	v_fmac_f32_e32 v55, v56, v52
	v_fma_f32 v50, -v50, v55, v54
	v_div_fmas_f32 v50, v50, v52, v55
	v_div_fixup_f32 v50, v50, v1, v91
	s_waitcnt vmcnt(16)
	v_pk_fma_f32 v[36:37], v[176:177], v[50:51], v[76:77] op_sel_hi:[1,0,1]
	v_pk_fma_f32 v[34:35], v[178:179], v[50:51], v[74:75] op_sel_hi:[1,0,1]
	s_waitcnt vmcnt(15)
	v_pk_fma_f32 v[40:41], v[172:173], v[50:51], v[80:81] op_sel_hi:[1,0,1]
	v_pk_fma_f32 v[38:39], v[174:175], v[50:51], v[78:79] op_sel_hi:[1,0,1]
	s_waitcnt vmcnt(14)
	v_pk_fma_f32 v[44:45], v[168:169], v[50:51], v[84:85] op_sel_hi:[1,0,1]
	v_pk_fma_f32 v[42:43], v[170:171], v[50:51], v[82:83] op_sel_hi:[1,0,1]
	s_waitcnt vmcnt(13)
	v_pk_fma_f32 v[48:49], v[164:165], v[50:51], v[88:89] op_sel_hi:[1,0,1]
	v_pk_fma_f32 v[46:47], v[166:167], v[50:51], v[86:87] op_sel_hi:[1,0,1]
	global_store_dwordx4 v[110:111], v[34:37], off
	global_store_dwordx4 v[110:111], v[38:41], off offset:64
	global_store_dwordx4 v[110:111], v[42:45], off offset:128
	global_store_dwordx4 v[110:111], v[46:49], off offset:192
	s_nop 1
	v_permlane16_swap_b32 v120, v53
	s_lshl_b32 s16, s39, 1
	v_add_f32_e32 v1, v120, v53
	v_mov_b32_e32 v50, v1
	s_nop 1
	v_permlane32_swap_b32 v50, v1
	s_addk_i32 s17, 0xfe01
	v_add_f32_e32 v1, v50, v1
	s_or_b32 s18, s16, 1
	s_lshr_b32 s25, s17, 6
	v_max_f32_e32 v1, 0xda24260, v1
	s_sub_i32 s27, s18, s25
	s_cmp_gt_i32 s27, -1
	s_waitcnt vmcnt(16)
	v_div_scale_f32 v50, s[18:19], v1, v1, v92
	v_rcp_f32_e32 v52, v50
	v_div_scale_f32 v53, vcc, v92, v1, v92
	v_fma_f32 v54, -v50, v52, 1.0
	v_fmac_f32_e32 v52, v54, v52
	v_mul_f32_e32 v54, v53, v52
	v_fma_f32 v55, -v50, v54, v53
	v_fmac_f32_e32 v54, v55, v52
	v_fma_f32 v50, -v50, v54, v53
	v_div_fmas_f32 v50, v50, v52, v54
	v_div_fixup_f32 v50, v50, v1, v92
	s_waitcnt vmcnt(15)
	v_pk_fma_f32 v[36:37], v[160:161], v[50:51], v[238:239] op_sel_hi:[1,0,1]
	v_pk_fma_f32 v[34:35], v[162:163], v[50:51], v[236:237] op_sel_hi:[1,0,1]
	s_waitcnt vmcnt(14)
	v_pk_fma_f32 v[40:41], v[156:157], v[50:51], v[242:243] op_sel_hi:[1,0,1]
	v_pk_fma_f32 v[38:39], v[158:159], v[50:51], v[240:241] op_sel_hi:[1,0,1]
	s_waitcnt vmcnt(13)
	v_pk_fma_f32 v[44:45], v[152:153], v[50:51], v[246:247] op_sel_hi:[1,0,1]
	v_pk_fma_f32 v[42:43], v[154:155], v[50:51], v[244:245] op_sel_hi:[1,0,1]
	s_waitcnt vmcnt(12)
	v_pk_fma_f32 v[48:49], v[148:149], v[50:51], v[250:251] op_sel_hi:[1,0,1]
	v_pk_fma_f32 v[46:47], v[150:151], v[50:51], v[248:249] op_sel_hi:[1,0,1]
	global_store_dwordx4 v[108:109], v[34:37], off
	global_store_dwordx4 v[108:109], v[38:41], off offset:64
	global_store_dwordx4 v[108:109], v[42:45], off offset:128
	global_store_dwordx4 v[108:109], v[46:49], off offset:192
	s_cbranch_scc0 .LBB0_2914
	s_and_b32 s18, s17, 0xffffffc0
	v_or_b32_e32 v34, s18, v214
	v_mov_b32_e32 v35, 0
	v_lshlrev_b64 v[36:37], 7, v[34:35]
	s_mov_b32 s19, 0
	v_lshl_add_u64 v[36:37], s[22:23], 0, v[36:37]
	v_mov_b32_e32 v131, v35
	v_lshl_add_u64 v[34:35], v[36:37], 0, v[130:131]
	v_lshl_add_u64 v[36:37], s[18:19], 1, v[132:133]
	v_lshl_add_u64 v[38:39], v[36:37], 0, v[130:131]
	global_load_dwordx4 v[34:37], v[34:35], off
	s_nop 0
	global_load_dwordx4 v[38:41], v[38:39], off
	s_mov_b32 s17, 0x12c00
	v_add3_u32 v1, v229, v220, s17
	s_waitcnt vmcnt(1)
	ds_write_b128 v228, v[34:37]
	s_waitcnt vmcnt(0)
	ds_write_b128 v1, v[38:41]

.LBB0_2928:
	global_load_dword v98, v[106:107], off offset:128
	global_load_dword v99, v[106:107], off offset:132
	global_load_dword v100, v[106:107], off offset:136
	global_load_dword v101, v[106:107], off offset:140
	global_load_dwordx4 v[164:167], v[114:115], off
	global_load_dwordx4 v[168:171], v[114:115], off offset:64
	global_load_dwordx4 v[172:175], v[114:115], off offset:128
	global_load_dwordx4 v[176:179], v[114:115], off offset:192
	global_load_dwordx4 v[180:183], v[112:113], off
	global_load_dwordx4 v[184:187], v[112:113], off offset:64
	global_load_dwordx4 v[188:191], v[112:113], off offset:128
	global_load_dwordx4 v[192:195], v[112:113], off offset:192
	global_load_dwordx4 v[196:199], v[110:111], off
	global_load_dwordx4 v[200:203], v[110:111], off offset:64
	global_load_dwordx4 v[204:207], v[110:111], off offset:128
	global_load_dwordx4 v[208:211], v[110:111], off offset:192
	global_load_dwordx4 v[228:231], v[108:109], off
	global_load_dwordx4 v[232:235], v[108:109], off offset:64
	global_load_dwordx4 v[236:239], v[108:109], off offset:128
	global_load_dwordx4 v[240:243], v[108:109], off offset:192
	v_mov_b32_e32 v1, v2
	s_nop 1
	v_permlane16_swap_b32 v2, v1
	v_readlane_b32 s16, v254, 12
	v_add_f32_e32 v1, v2, v1
	v_mov_b32_e32 v8, v1
	s_nop 1
	v_permlane32_swap_b32 v8, v1
	v_add_f32_e32 v1, v8, v1
	v_readlane_b32 s17, v254, 13
	v_max_f32_e32 v1, 0xda24260, v1
	s_mov_b32 s57, 0
	v_lshl_add_u64 v[2:3], v[118:119], 1, s[16:17]
	v_lshl_add_u64 v[2:3], v[116:117], 1, v[2:3]
	v_lshl_add_u64 v[8:9], v[2:3], 0, s[56:57]
	s_mov_b32 s63, s57
	s_mov_b32 s61, s57
	s_mov_b32 s59, s57
	s_sub_i32 s24, 31, s39
	s_lshl_b32 s25, s24, 7
	v_mov_b32_e32 v156, v146
	s_add_i32 s3, s3, s25
	v_mov_b32_e32 v131, 0
	s_waitcnt vmcnt(16)
	v_div_scale_f32 v11, s[16:17], v1, v1, v98
	v_rcp_f32_e32 v12, v11
	v_div_scale_f32 v13, vcc, v98, v1, v98
	v_fma_f32 v14, -v11, v12, 1.0
	v_fmac_f32_e32 v12, v14, v12
	v_mul_f32_e32 v14, v13, v12
	v_fma_f32 v15, -v11, v14, v13
	v_fmac_f32_e32 v14, v15, v12
	v_fma_f32 v11, -v11, v14, v13
	v_div_fmas_f32 v11, v11, v12, v14
	v_div_fixup_f32 v10, v11, v1, v98
	s_waitcnt vmcnt(15)
	v_pk_fma_f32 v[6:7], v[96:97], v[10:11], v[166:167] op_sel_hi:[1,0,1]
	v_pk_fma_f32 v[4:5], v[94:95], v[10:11], v[164:165] op_sel_hi:[1,0,1]
	v_mov_b32_e32 v1, v122
	v_cvt_pk_bf16_f32 v4, v4, v5
	v_cvt_pk_bf16_f32 v5, v6, v7
	global_store_dwordx2 v[8:9], v[4:5], off
	s_waitcnt vmcnt(15)
	v_pk_fma_f32 v[6:7], v[92:93], v[10:11], v[170:171] op_sel_hi:[1,0,1]
	v_pk_fma_f32 v[4:5], v[90:91], v[10:11], v[168:169] op_sel_hi:[1,0,1]
	s_nop 0
	v_cvt_pk_bf16_f32 v4, v4, v5
	v_cvt_pk_bf16_f32 v5, v6, v7
	global_store_dwordx2 v[8:9], v[4:5], off offset:32
	s_waitcnt vmcnt(15)
	v_pk_fma_f32 v[6:7], v[88:89], v[10:11], v[174:175] op_sel_hi:[1,0,1]
	v_pk_fma_f32 v[4:5], v[86:87], v[10:11], v[172:173] op_sel_hi:[1,0,1]
	s_nop 0
	v_cvt_pk_bf16_f32 v4, v4, v5
	v_cvt_pk_bf16_f32 v5, v6, v7
	global_store_dwordx2 v[8:9], v[4:5], off offset:64
	s_waitcnt vmcnt(15)
	v_pk_fma_f32 v[6:7], v[84:85], v[10:11], v[178:179] op_sel_hi:[1,0,1]
	v_pk_fma_f32 v[4:5], v[82:83], v[10:11], v[176:177] op_sel_hi:[1,0,1]
	s_nop 0
	v_cvt_pk_bf16_f32 v4, v4, v5
	v_cvt_pk_bf16_f32 v5, v6, v7
	global_store_dwordx2 v[8:9], v[4:5], off offset:96
	s_nop 1
	v_permlane16_swap_b32 v122, v1
	s_nop 0
	v_add_f32_e32 v1, v122, v1
	v_mov_b32_e32 v8, v1
	s_nop 1
	v_permlane32_swap_b32 v8, v1
	v_add_f32_e32 v1, v8, v1
	v_max_f32_e32 v1, 0xda24260, v1
	v_lshl_add_u64 v[8:9], v[2:3], 0, s[62:63]
	s_waitcnt vmcnt(16)
	v_div_scale_f32 v11, s[16:17], v1, v1, v99
	v_rcp_f32_e32 v12, v11
	v_div_scale_f32 v13, vcc, v99, v1, v99
	v_fma_f32 v14, -v11, v12, 1.0
	v_fmac_f32_e32 v12, v14, v12
	v_mul_f32_e32 v14, v13, v12
	v_fma_f32 v15, -v11, v14, v13
	v_fmac_f32_e32 v14, v15, v12
	v_fma_f32 v11, -v11, v14, v13
	v_div_fmas_f32 v11, v11, v12, v14
	v_div_fixup_f32 v10, v11, v1, v99
	s_waitcnt vmcnt(15)
	v_pk_fma_f32 v[6:7], v[80:81], v[10:11], v[182:183] op_sel_hi:[1,0,1]
	v_pk_fma_f32 v[4:5], v[78:79], v[10:11], v[180:181] op_sel_hi:[1,0,1]
	v_mov_b32_e32 v1, v121
	v_cvt_pk_bf16_f32 v4, v4, v5
	v_cvt_pk_bf16_f32 v5, v6, v7
	global_store_dwordx2 v[8:9], v[4:5], off
	s_waitcnt vmcnt(15)
	v_pk_fma_f32 v[6:7], v[76:77], v[10:11], v[186:187] op_sel_hi:[1,0,1]
	v_pk_fma_f32 v[4:5], v[74:75], v[10:11], v[184:185] op_sel_hi:[1,0,1]
	s_nop 0
	v_cvt_pk_bf16_f32 v4, v4, v5
	v_cvt_pk_bf16_f32 v5, v6, v7
	global_store_dwordx2 v[8:9], v[4:5], off offset:32
	s_waitcnt vmcnt(15)
	v_pk_fma_f32 v[6:7], v[72:73], v[10:11], v[190:191] op_sel_hi:[1,0,1]
	v_pk_fma_f32 v[4:5], v[70:71], v[10:11], v[188:189] op_sel_hi:[1,0,1]
	s_nop 0
	v_cvt_pk_bf16_f32 v4, v4, v5
	v_cvt_pk_bf16_f32 v5, v6, v7
	global_store_dwordx2 v[8:9], v[4:5], off offset:64
	s_waitcnt vmcnt(15)
	v_pk_fma_f32 v[6:7], v[68:69], v[10:11], v[194:195] op_sel_hi:[1,0,1]
	v_pk_fma_f32 v[4:5], v[66:67], v[10:11], v[192:193] op_sel_hi:[1,0,1]
	s_nop 0
	v_cvt_pk_bf16_f32 v4, v4, v5
	v_cvt_pk_bf16_f32 v5, v6, v7
	global_store_dwordx2 v[8:9], v[4:5], off offset:96
	s_nop 1
	v_permlane16_swap_b32 v121, v1
	s_nop 0
	v_add_f32_e32 v1, v121, v1
	v_mov_b32_e32 v8, v1
	s_nop 1
	v_permlane32_swap_b32 v1, v8
	v_add_f32_e32 v1, v1, v8
	v_max_f32_e32 v1, 0xda24260, v1
	v_lshl_add_u64 v[8:9], v[2:3], 0, s[60:61]
	s_waitcnt vmcnt(16)
	v_div_scale_f32 v11, s[16:17], v1, v1, v100
	v_rcp_f32_e32 v12, v11
	v_div_scale_f32 v13, vcc, v100, v1, v100
	v_fma_f32 v14, -v11, v12, 1.0
	v_fmac_f32_e32 v12, v14, v12
	v_mul_f32_e32 v14, v13, v12
	v_fma_f32 v15, -v11, v14, v13
	v_fmac_f32_e32 v14, v15, v12
	v_fma_f32 v11, -v11, v14, v13
	v_div_fmas_f32 v11, v11, v12, v14
	v_div_fixup_f32 v10, v11, v1, v100
	s_waitcnt vmcnt(15)
	v_pk_fma_f32 v[6:7], v[64:65], v[10:11], v[198:199] op_sel_hi:[1,0,1]
	v_pk_fma_f32 v[4:5], v[62:63], v[10:11], v[196:197] op_sel_hi:[1,0,1]
	v_mov_b32_e32 v1, v120
	v_cvt_pk_bf16_f32 v4, v4, v5
	v_cvt_pk_bf16_f32 v5, v6, v7
	global_store_dwordx2 v[8:9], v[4:5], off
	s_waitcnt vmcnt(15)
	v_pk_fma_f32 v[6:7], v[60:61], v[10:11], v[202:203] op_sel_hi:[1,0,1]
	v_pk_fma_f32 v[4:5], v[58:59], v[10:11], v[200:201] op_sel_hi:[1,0,1]
	s_nop 0
	v_cvt_pk_bf16_f32 v4, v4, v5
	v_cvt_pk_bf16_f32 v5, v6, v7
	global_store_dwordx2 v[8:9], v[4:5], off offset:32
	s_waitcnt vmcnt(15)
	v_pk_fma_f32 v[6:7], v[56:57], v[10:11], v[206:207] op_sel_hi:[1,0,1]
	v_pk_fma_f32 v[4:5], v[54:55], v[10:11], v[204:205] op_sel_hi:[1,0,1]
	s_nop 0
	v_cvt_pk_bf16_f32 v4, v4, v5
	v_cvt_pk_bf16_f32 v5, v6, v7
	global_store_dwordx2 v[8:9], v[4:5], off offset:64
	s_waitcnt vmcnt(15)
	v_pk_fma_f32 v[6:7], v[52:53], v[10:11], v[210:211] op_sel_hi:[1,0,1]
	v_pk_fma_f32 v[4:5], v[50:51], v[10:11], v[208:209] op_sel_hi:[1,0,1]
	s_nop 0
	v_cvt_pk_bf16_f32 v4, v4, v5
	v_cvt_pk_bf16_f32 v5, v6, v7
	global_store_dwordx2 v[8:9], v[4:5], off offset:96
	s_nop 1
	v_permlane16_swap_b32 v120, v1
	s_nop 0
	v_add_f32_e32 v1, v120, v1
	v_mov_b32_e32 v8, v1
	s_nop 1
	v_permlane32_swap_b32 v8, v1
	v_add_f32_e32 v1, v8, v1
	v_max_f32_e32 v1, 0xda24260, v1
	v_lshl_add_u64 v[8:9], v[2:3], 0, s[58:59]
	s_waitcnt vmcnt(16)
	v_div_scale_f32 v11, s[16:17], v1, v1, v101
	v_rcp_f32_e32 v12, v11
	v_div_scale_f32 v2, vcc, v101, v1, v101
	s_add_i32 s16, s3, s37
	v_fma_f32 v3, -v11, v12, 1.0
	v_fmac_f32_e32 v12, v3, v12
	v_mul_f32_e32 v3, v2, v12
	v_fma_f32 v13, -v11, v3, v2
	v_fmac_f32_e32 v3, v13, v12
	v_fma_f32 v2, -v11, v3, v2
	v_div_fmas_f32 v2, v2, v12, v3
	v_div_fixup_f32 v10, v2, v1, v101
	s_waitcnt vmcnt(15)
	v_pk_fma_f32 v[2:3], v[48:49], v[10:11], v[230:231] op_sel_hi:[1,0,1]
	v_pk_fma_f32 v[4:5], v[46:47], v[10:11], v[228:229] op_sel_hi:[1,0,1]
	v_mov_b32_e32 v1, 0
	v_cvt_pk_bf16_f32 v4, v4, v5
	v_cvt_pk_bf16_f32 v5, v2, v3
	global_store_dwordx2 v[8:9], v[4:5], off
	s_waitcnt vmcnt(15)
	v_pk_fma_f32 v[4:5], v[44:45], v[10:11], v[234:235] op_sel_hi:[1,0,1]
	v_pk_fma_f32 v[2:3], v[42:43], v[10:11], v[232:233] op_sel_hi:[1,0,1]
	s_nop 0
	v_cvt_pk_bf16_f32 v2, v2, v3
	v_cvt_pk_bf16_f32 v3, v4, v5
	global_store_dwordx2 v[8:9], v[2:3], off offset:32
	s_waitcnt vmcnt(15)
	v_pk_fma_f32 v[4:5], v[40:41], v[10:11], v[238:239] op_sel_hi:[1,0,1]
	v_pk_fma_f32 v[2:3], v[38:39], v[10:11], v[236:237] op_sel_hi:[1,0,1]
	s_nop 0
	v_cvt_pk_bf16_f32 v2, v2, v3
	v_cvt_pk_bf16_f32 v3, v4, v5
	global_store_dwordx2 v[8:9], v[2:3], off offset:64
	s_waitcnt vmcnt(15)
	v_pk_fma_f32 v[4:5], v[36:37], v[10:11], v[242:243] op_sel_hi:[1,0,1]
	v_pk_fma_f32 v[2:3], v[34:35], v[10:11], v[240:241] op_sel_hi:[1,0,1]
	s_nop 0
	v_cvt_pk_bf16_f32 v2, v2, v3
	v_cvt_pk_bf16_f32 v3, v4, v5
	global_store_dwordx2 v[8:9], v[2:3], off offset:96
	s_barrier
	s_nop 0
	v_and_b32_e32 v208, 15, v156
	v_or_b32_e32 v148, s16, v208
	v_ashrrev_i32_e32 v158, 4, v156
	v_ashrrev_i32_e32 v149, 31, v148
	v_lshlrev_b32_e32 v144, 3, v158
	v_lshlrev_b64 v[2:3], 11, v[148:149]
	v_ashrrev_i32_e32 v145, 31, v144
	v_lshl_add_u64 v[2:3], s[54:55], 0, v[2:3]
	v_lshl_add_u64 v[2:3], v[144:145], 1, v[2:3]
	v_lshl_add_u64 v[6:7], v[2:3], 0, s[56:57]
	v_lshl_add_u64 v[14:15], v[2:3], 0, s[62:63]
	v_lshl_add_u64 v[22:23], v[2:3], 0, s[60:61]
	v_lshl_add_u64 v[30:31], v[2:3], 0, s[58:59]
	global_load_dwordx4 v[2:5], v[6:7], off
	s_nop 0
	global_load_dwordx4 v[6:9], v[6:7], off offset:64
	s_nop 0
	global_load_dwordx4 v[10:13], v[14:15], off
	s_nop 0
	global_load_dwordx4 v[14:17], v[14:15], off offset:64
	s_nop 0
	global_load_dwordx4 v[18:21], v[22:23], off
	s_nop 0
	global_load_dwordx4 v[22:25], v[22:23], off offset:64
	s_nop 0
	global_load_dwordx4 v[26:29], v[30:31], off
	s_nop 0
	global_load_dwordx4 v[30:33], v[30:31], off offset:64
	s_movk_i32 s16, 0x840
	v_cmp_gt_i32_e32 vcc, s16, v156
	s_and_saveexec_b64 s[16:17], vcc
	s_cbranch_execz .LBB0_2931
	v_lshlrev_b32_e32 v35, 2, v156
	v_readlane_b32 s18, v254, 60
	v_subrev_u32_e32 v34, 64, v156
	s_movk_i32 s20, 0x7ff
	v_add3_u32 v35, s18, v35, v131
	s_mov_b64 s[18:19], 0

.LBB0_2955:
	v_readlane_b32 s16, v254, 14
	v_readlane_b32 s17, v254, 15
	s_movk_i32 s14, 0xc0
	s_mov_b32 s65, 0
	v_mov_b64_e32 v[98:99], s[16:17]
	v_mad_i64_i32 v[98:99], s[14:15], v148, s14, v[98:99]
	s_waitcnt vmcnt(1)
	v_lshl_add_u64 v[106:107], v[98:99], 0, s[64:65]
	global_load_dword v98, v[106:107], off
	global_load_dword v162, v[106:107], off offset:4
	global_load_dword v164, v[106:107], off offset:8
	global_load_dword v166, v[106:107], off offset:12
	v_readlane_b32 s14, v254, 16
	s_waitcnt vmcnt(1)
	v_lshlrev_b64 v[100:101], 12, v[148:149]
	v_lshlrev_b32_e32 v116, 2, v158
	v_readlane_b32 s15, v254, 17
	v_ashrrev_i32_e32 v117, 31, v116
	s_mov_b32 s69, s65
	v_lshl_add_u64 v[100:101], s[14:15], 0, v[100:101]
	v_lshl_add_u64 v[100:101], v[116:117], 2, v[100:101]
	v_lshl_add_u64 v[114:115], v[100:101], 0, s[68:69]
	s_mov_b32 s71, s65
	v_lshl_add_u64 v[112:113], v[100:101], 0, s[70:71]
	s_mov_b32 s73, s65
	v_lshl_add_u64 v[110:111], v[100:101], 0, s[72:73]
	s_mov_b32 s67, s65
	s_ashr_i32 s27, s3, 6
	v_lshl_add_u64 v[108:109], v[100:101], 0, s[66:67]
	s_add_i32 s37, s27, -1
	v_cmp_gt_u32_e32 vcc, 16, v156
	s_waitcnt vmcnt(3)
	v_pk_mul_f32 v[96:97], v[96:97], v[98:99] op_sel_hi:[1,0]
	v_pk_mul_f32 v[94:95], v[94:95], v[98:99] op_sel_hi:[1,0]
	v_pk_mul_f32 v[92:93], v[92:93], v[98:99] op_sel_hi:[1,0]
	v_pk_mul_f32 v[90:91], v[90:91], v[98:99] op_sel_hi:[1,0]
	v_pk_mul_f32 v[88:89], v[88:89], v[98:99] op_sel_hi:[1,0]
	v_pk_mul_f32 v[86:87], v[86:87], v[98:99] op_sel_hi:[1,0]
	v_pk_mul_f32 v[84:85], v[84:85], v[98:99] op_sel_hi:[1,0]
	v_pk_mul_f32 v[82:83], v[82:83], v[98:99] op_sel_hi:[1,0]
	global_store_dwordx4 v[114:115], v[94:97], off
	global_store_dwordx4 v[114:115], v[90:93], off offset:64
	global_store_dwordx4 v[114:115], v[86:89], off offset:128
	global_store_dwordx4 v[114:115], v[82:85], off offset:192
	s_waitcnt vmcnt(6)
	v_pk_mul_f32 v[80:81], v[80:81], v[162:163] op_sel_hi:[1,0]
	v_pk_mul_f32 v[78:79], v[78:79], v[162:163] op_sel_hi:[1,0]
	v_pk_mul_f32 v[76:77], v[76:77], v[162:163] op_sel_hi:[1,0]
	v_pk_mul_f32 v[74:75], v[74:75], v[162:163] op_sel_hi:[1,0]
	v_pk_mul_f32 v[72:73], v[72:73], v[162:163] op_sel_hi:[1,0]
	v_pk_mul_f32 v[70:71], v[70:71], v[162:163] op_sel_hi:[1,0]
	v_pk_mul_f32 v[68:69], v[68:69], v[162:163] op_sel_hi:[1,0]
	v_pk_mul_f32 v[66:67], v[66:67], v[162:163] op_sel_hi:[1,0]
	global_store_dwordx4 v[112:113], v[78:81], off
	global_store_dwordx4 v[112:113], v[74:77], off offset:64
	global_store_dwordx4 v[112:113], v[70:73], off offset:128
	global_store_dwordx4 v[112:113], v[66:69], off offset:192
	s_waitcnt vmcnt(9)
	v_pk_mul_f32 v[64:65], v[64:65], v[164:165] op_sel_hi:[1,0]
	v_pk_mul_f32 v[62:63], v[62:63], v[164:165] op_sel_hi:[1,0]
	v_pk_mul_f32 v[60:61], v[60:61], v[164:165] op_sel_hi:[1,0]
	v_pk_mul_f32 v[58:59], v[58:59], v[164:165] op_sel_hi:[1,0]
	v_pk_mul_f32 v[56:57], v[56:57], v[164:165] op_sel_hi:[1,0]
	v_pk_mul_f32 v[54:55], v[54:55], v[164:165] op_sel_hi:[1,0]
	v_pk_mul_f32 v[52:53], v[52:53], v[164:165] op_sel_hi:[1,0]
	v_pk_mul_f32 v[50:51], v[50:51], v[164:165] op_sel_hi:[1,0]
	global_store_dwordx4 v[110:111], v[62:65], off
	global_store_dwordx4 v[110:111], v[58:61], off offset:64
	global_store_dwordx4 v[110:111], v[54:57], off offset:128
	global_store_dwordx4 v[110:111], v[50:53], off offset:192
	s_waitcnt vmcnt(12)
	v_pk_mul_f32 v[48:49], v[48:49], v[166:167] op_sel_hi:[1,0]
	v_pk_mul_f32 v[46:47], v[46:47], v[166:167] op_sel_hi:[1,0]
	v_lshlrev_b32_e32 v50, 5, v158
	v_pk_mul_f32 v[44:45], v[44:45], v[166:167] op_sel_hi:[1,0]
	v_pk_mul_f32 v[42:43], v[42:43], v[166:167] op_sel_hi:[1,0]
	v_pk_mul_f32 v[40:41], v[40:41], v[166:167] op_sel_hi:[1,0]
	v_pk_mul_f32 v[38:39], v[38:39], v[166:167] op_sel_hi:[1,0]
	v_pk_mul_f32 v[36:37], v[36:37], v[166:167] op_sel_hi:[1,0]
	v_pk_mul_f32 v[34:35], v[34:35], v[166:167] op_sel_hi:[1,0]
	global_store_dwordx4 v[108:109], v[46:49], off
	global_store_dwordx4 v[108:109], v[42:45], off offset:64
	global_store_dwordx4 v[108:109], v[38:41], off offset:128
	global_store_dwordx4 v[108:109], v[34:37], off offset:192
	s_waitcnt lgkmcnt(0)
	v_cmp_eq_u32_e64 s[14:15], s27, v50
	v_cmp_eq_u32_e64 s[16:17], s37, v50
	s_or_b64 s[14:15], s[14:15], s[16:17]
	s_nor_b64 s[14:15], vcc, s[14:15]
	s_and_saveexec_b64 s[16:17], s[14:15]
	s_xor_b64 s[16:17], exec, s[16:17]
	s_cbranch_execz .LBB0_2957
	v_lshl_add_u32 v1, v50, 2, v159
	ds_read_b32 v1, v1
	v_sub_u32_e32 v34, 0x7f, v50
	s_movk_i32 s14, 0xff80
	s_waitcnt lgkmcnt(0)
	v_and_or_b32 v1, v1, s14, v34
	v_add_u32_e32 v1, 0x80, v1
	v_cmp_ge_i32_e64 s[14:15], s27, v50
	s_nop 1
	v_cndmask_b32_e64 v37, 0, v1, s[14:15]

.LBB0_3115:
	v_mov_b32_e32 v1, v123
	s_nop 1
	v_permlane16_swap_b32 v123, v1
	v_mov_b32_e32 v53, v122
	v_add_f32_e32 v1, v123, v1
	v_mov_b32_e32 v50, v1
	s_nop 1
	v_permlane32_swap_b32 v50, v1
	global_load_dword v51, v[106:107], off offset:64
	global_load_dwordx4 v[34:37], v[114:115], off
	global_load_dwordx4 v[38:41], v[114:115], off offset:64
	global_load_dwordx4 v[42:45], v[114:115], off offset:128
	global_load_dwordx4 v[46:49], v[114:115], off offset:192
	global_load_dword v90, v[106:107], off offset:68
	global_load_dwordx4 v[58:61], v[112:113], off
	global_load_dwordx4 v[62:65], v[112:113], off offset:64
	global_load_dwordx4 v[66:69], v[112:113], off offset:128
	global_load_dwordx4 v[70:73], v[112:113], off offset:192
	global_load_dword v91, v[106:107], off offset:72
	global_load_dwordx4 v[74:77], v[110:111], off
	global_load_dwordx4 v[78:81], v[110:111], off offset:64
	global_load_dwordx4 v[82:85], v[110:111], off offset:128
	global_load_dwordx4 v[86:89], v[110:111], off offset:192
	global_load_dword v92, v[106:107], off offset:76
	global_load_dwordx4 v[236:239], v[108:109], off
	global_load_dwordx4 v[240:243], v[108:109], off offset:64
	global_load_dwordx4 v[244:247], v[108:109], off offset:128
	global_load_dwordx4 v[248:251], v[108:109], off offset:192
	v_add_f32_e32 v1, v50, v1
	v_max_f32_e32 v1, 0xda24260, v1
	s_waitcnt vmcnt(19)
	v_div_scale_f32 v50, s[0:1], v1, v1, v51
	v_rcp_f32_e32 v52, v50
	v_div_scale_f32 v54, vcc, v51, v1, v51
	v_fma_f32 v55, -v50, v52, 1.0
	v_fmac_f32_e32 v52, v55, v52
	v_mul_f32_e32 v55, v54, v52
	v_fma_f32 v56, -v50, v55, v54
	v_fmac_f32_e32 v55, v56, v52
	v_fma_f32 v50, -v50, v55, v54
	v_div_fmas_f32 v50, v50, v52, v55
	v_div_fixup_f32 v50, v50, v1, v51
	s_waitcnt vmcnt(18)
	v_pk_fma_f32 v[36:37], v[192:193], v[50:51], v[36:37] op_sel_hi:[1,0,1]
	v_pk_fma_f32 v[34:35], v[194:195], v[50:51], v[34:35] op_sel_hi:[1,0,1]
	s_waitcnt vmcnt(17)
	v_pk_fma_f32 v[40:41], v[196:197], v[50:51], v[40:41] op_sel_hi:[1,0,1]
	v_pk_fma_f32 v[38:39], v[198:199], v[50:51], v[38:39] op_sel_hi:[1,0,1]
	s_waitcnt vmcnt(16)
	v_pk_fma_f32 v[44:45], v[200:201], v[50:51], v[44:45] op_sel_hi:[1,0,1]
	v_pk_fma_f32 v[42:43], v[202:203], v[50:51], v[42:43] op_sel_hi:[1,0,1]
	s_waitcnt vmcnt(15)
	v_pk_fma_f32 v[48:49], v[204:205], v[50:51], v[48:49] op_sel_hi:[1,0,1]
	v_pk_fma_f32 v[46:47], v[206:207], v[50:51], v[46:47] op_sel_hi:[1,0,1]
	global_store_dwordx4 v[114:115], v[34:37], off
	global_store_dwordx4 v[114:115], v[38:41], off offset:64
	global_store_dwordx4 v[114:115], v[42:45], off offset:128
	global_store_dwordx4 v[114:115], v[46:49], off offset:192
	s_nop 1
	v_permlane16_swap_b32 v122, v53
	s_nop 0
	v_add_f32_e32 v1, v122, v53
	v_mov_b32_e32 v50, v1
	s_nop 1
	v_permlane32_swap_b32 v1, v50
	v_add_f32_e32 v1, v1, v50
	v_max_f32_e32 v1, 0xda24260, v1
	v_mov_b32_e32 v53, v121
	s_waitcnt vmcnt(18)
	v_div_scale_f32 v50, s[0:1], v1, v1, v90
	v_rcp_f32_e32 v52, v50
	v_div_scale_f32 v54, vcc, v90, v1, v90
	v_fma_f32 v55, -v50, v52, 1.0
	v_fmac_f32_e32 v52, v55, v52
	v_mul_f32_e32 v55, v54, v52
	v_fma_f32 v56, -v50, v55, v54
	v_fmac_f32_e32 v55, v56, v52
	v_fma_f32 v50, -v50, v55, v54
	v_div_fmas_f32 v50, v50, v52, v55
	v_div_fixup_f32 v50, v50, v1, v90
	s_waitcnt vmcnt(17)
	v_pk_fma_f32 v[36:37], v[176:177], v[50:51], v[60:61] op_sel_hi:[1,0,1]
	v_pk_fma_f32 v[34:35], v[178:179], v[50:51], v[58:59] op_sel_hi:[1,0,1]
	s_waitcnt vmcnt(16)
	v_pk_fma_f32 v[40:41], v[180:181], v[50:51], v[64:65] op_sel_hi:[1,0,1]
	v_pk_fma_f32 v[38:39], v[182:183], v[50:51], v[62:63] op_sel_hi:[1,0,1]
	s_waitcnt vmcnt(15)
	v_pk_fma_f32 v[44:45], v[184:185], v[50:51], v[68:69] op_sel_hi:[1,0,1]
	v_pk_fma_f32 v[42:43], v[186:187], v[50:51], v[66:67] op_sel_hi:[1,0,1]
	s_waitcnt vmcnt(14)
	v_pk_fma_f32 v[48:49], v[188:189], v[50:51], v[72:73] op_sel_hi:[1,0,1]
	v_pk_fma_f32 v[46:47], v[190:191], v[50:51], v[70:71] op_sel_hi:[1,0,1]
	global_store_dwordx4 v[112:113], v[34:37], off
	global_store_dwordx4 v[112:113], v[38:41], off offset:64
	global_store_dwordx4 v[112:113], v[42:45], off offset:128
	global_store_dwordx4 v[112:113], v[46:49], off offset:192
	s_nop 1
	v_permlane16_swap_b32 v121, v53
	s_nop 0
	v_add_f32_e32 v1, v121, v53
	v_mov_b32_e32 v50, v1
	s_nop 1
	v_permlane32_swap_b32 v50, v1
	v_add_f32_e32 v1, v50, v1
	v_max_f32_e32 v1, 0xda24260, v1
	v_mov_b32_e32 v53, v120
	s_waitcnt vmcnt(17)
	v_div_scale_f32 v50, s[0:1], v1, v1, v91
	v_rcp_f32_e32 v52, v50
	v_div_scale_f32 v54, vcc, v91, v1, v91
	s_max_i32 s1, s25, 0x1ff
	v_fma_f32 v55, -v50, v52, 1.0
	v_fmac_f32_e32 v52, v55, v52
	v_mul_f32_e32 v55, v54, v52
	v_fma_f32 v56, -v50, v55, v54
	v_fmac_f32_e32 v55, v56, v52
	v_fma_f32 v50, -v50, v55, v54
	v_div_fmas_f32 v50, v50, v52, v55
	v_div_fixup_f32 v50, v50, v1, v91
	s_waitcnt vmcnt(16)
	v_pk_fma_f32 v[36:37], v[170:171], v[50:51], v[76:77] op_sel_hi:[1,0,1]
	v_pk_fma_f32 v[34:35], v[172:173], v[50:51], v[74:75] op_sel_hi:[1,0,1]
	s_waitcnt vmcnt(15)
	v_pk_fma_f32 v[40:41], v[166:167], v[50:51], v[80:81] op_sel_hi:[1,0,1]
	v_pk_fma_f32 v[38:39], v[168:169], v[50:51], v[78:79] op_sel_hi:[1,0,1]
	s_waitcnt vmcnt(14)
	v_pk_fma_f32 v[44:45], v[162:163], v[50:51], v[84:85] op_sel_hi:[1,0,1]
	v_pk_fma_f32 v[42:43], v[164:165], v[50:51], v[82:83] op_sel_hi:[1,0,1]
	s_waitcnt vmcnt(13)
	v_pk_fma_f32 v[48:49], v[158:159], v[50:51], v[88:89] op_sel_hi:[1,0,1]
	v_pk_fma_f32 v[46:47], v[160:161], v[50:51], v[86:87] op_sel_hi:[1,0,1]
	global_store_dwordx4 v[110:111], v[34:37], off
	global_store_dwordx4 v[110:111], v[38:41], off offset:64
	global_store_dwordx4 v[110:111], v[42:45], off offset:128
	global_store_dwordx4 v[110:111], v[46:49], off offset:192
	s_nop 1
	v_permlane16_swap_b32 v120, v53
	s_lshl_b32 s0, s24, 1
	v_add_f32_e32 v1, v120, v53
	v_mov_b32_e32 v50, v1
	s_nop 1
	v_permlane32_swap_b32 v1, v50
	s_addk_i32 s1, 0xfe01
	v_add_f32_e32 v1, v1, v50
	s_or_b32 s4, s0, 1
	s_lshr_b32 s8, s1, 6
	v_max_f32_e32 v1, 0xda24260, v1
	s_sub_i32 s9, s4, s8
	s_cmp_gt_i32 s9, -1
	s_waitcnt vmcnt(16)
	v_div_scale_f32 v50, s[4:5], v1, v1, v92
	v_rcp_f32_e32 v52, v50
	v_div_scale_f32 v53, vcc, v92, v1, v92
	v_fma_f32 v54, -v50, v52, 1.0
	v_fmac_f32_e32 v52, v54, v52
	v_mul_f32_e32 v54, v53, v52
	v_fma_f32 v55, -v50, v54, v53
	v_fmac_f32_e32 v54, v55, v52
	v_fma_f32 v50, -v50, v54, v53
	v_div_fmas_f32 v50, v50, v52, v54
	v_div_fixup_f32 v50, v50, v1, v92
	s_waitcnt vmcnt(15)
	v_pk_fma_f32 v[36:37], v[154:155], v[50:51], v[238:239] op_sel_hi:[1,0,1]
	v_pk_fma_f32 v[34:35], v[156:157], v[50:51], v[236:237] op_sel_hi:[1,0,1]
	s_waitcnt vmcnt(14)
	v_pk_fma_f32 v[40:41], v[150:151], v[50:51], v[242:243] op_sel_hi:[1,0,1]
	v_pk_fma_f32 v[38:39], v[152:153], v[50:51], v[240:241] op_sel_hi:[1,0,1]
	s_waitcnt vmcnt(13)
	v_pk_fma_f32 v[44:45], v[142:143], v[50:51], v[246:247] op_sel_hi:[1,0,1]
	v_pk_fma_f32 v[42:43], v[148:149], v[50:51], v[244:245] op_sel_hi:[1,0,1]
	s_waitcnt vmcnt(12)
	v_pk_fma_f32 v[48:49], v[138:139], v[50:51], v[250:251] op_sel_hi:[1,0,1]
	v_pk_fma_f32 v[46:47], v[140:141], v[50:51], v[248:249] op_sel_hi:[1,0,1]
	global_store_dwordx4 v[108:109], v[34:37], off
	global_store_dwordx4 v[108:109], v[38:41], off offset:64
	global_store_dwordx4 v[108:109], v[42:45], off offset:128
	global_store_dwordx4 v[108:109], v[46:49], off offset:192
	s_cbranch_scc0 .LBB0_3117
	s_and_b32 s4, s1, 0xffffffc0
	v_or_b32_e32 v34, s4, v214
	v_mov_b32_e32 v35, 0
	v_lshlrev_b64 v[36:37], 7, v[34:35]
	s_mov_b32 s5, 0
	v_lshl_add_u64 v[36:37], s[22:23], 0, v[36:37]
	v_mov_b32_e32 v131, v35
	v_lshl_add_u64 v[42:43], v[36:37], 0, v[130:131]
	v_lshl_add_u64 v[34:35], s[4:5], 1, v[132:133]
	v_lshl_add_u64 v[44:45], v[34:35], 0, v[130:131]
	global_load_dwordx4 v[34:37], v[42:43], off
	global_load_dwordx4 v[38:41], v[44:45], off
	s_waitcnt vmcnt(1)
	ds_write_b128 v212, v[34:37]
	s_waitcnt vmcnt(0)
	ds_write_b128 v213, v[38:41]

.LBB0_3131:
	global_load_dword v98, v[106:107], off offset:128
	global_load_dword v99, v[106:107], off offset:132
	global_load_dword v100, v[106:107], off offset:136
	global_load_dword v101, v[106:107], off offset:140
	global_load_dwordx4 v[164:167], v[114:115], off
	global_load_dwordx4 v[168:171], v[114:115], off offset:64
	global_load_dwordx4 v[172:175], v[114:115], off offset:128
	global_load_dwordx4 v[176:179], v[114:115], off offset:192
	global_load_dwordx4 v[180:183], v[112:113], off
	global_load_dwordx4 v[184:187], v[112:113], off offset:64
	global_load_dwordx4 v[188:191], v[112:113], off offset:128
	global_load_dwordx4 v[192:195], v[112:113], off offset:192
	global_load_dwordx4 v[196:199], v[110:111], off
	global_load_dwordx4 v[200:203], v[110:111], off offset:64
	global_load_dwordx4 v[204:207], v[110:111], off offset:128
	global_load_dwordx4 v[208:211], v[110:111], off offset:192
	global_load_dwordx4 v[228:231], v[108:109], off
	global_load_dwordx4 v[232:235], v[108:109], off offset:64
	global_load_dwordx4 v[236:239], v[108:109], off offset:128
	global_load_dwordx4 v[240:243], v[108:109], off offset:192
	v_mov_b32_e32 v1, v2
	s_nop 1
	v_permlane16_swap_b32 v2, v1
	v_readlane_b32 s0, v254, 12
	v_add_f32_e32 v1, v2, v1
	v_mov_b32_e32 v8, v1
	s_nop 1
	v_permlane32_swap_b32 v1, v8
	v_add_f32_e32 v1, v1, v8
	v_readlane_b32 s1, v254, 13
	v_max_f32_e32 v1, 0xda24260, v1
	s_mov_b32 s57, 0
	v_lshl_add_u64 v[2:3], v[118:119], 1, s[0:1]
	v_lshl_add_u64 v[2:3], v[116:117], 1, v[2:3]
	v_lshl_add_u64 v[8:9], v[2:3], 0, s[56:57]
	s_mov_b32 s63, s57
	s_mov_b32 s61, s57
	s_mov_b32 s59, s57
	s_waitcnt vmcnt(16)
	v_div_scale_f32 v11, s[0:1], v1, v1, v98
	v_rcp_f32_e32 v12, v11
	v_div_scale_f32 v13, vcc, v98, v1, v98
	v_fma_f32 v14, -v11, v12, 1.0
	v_fmac_f32_e32 v12, v14, v12
	v_mul_f32_e32 v14, v13, v12
	v_fma_f32 v15, -v11, v14, v13
	v_fmac_f32_e32 v14, v15, v12
	v_fma_f32 v11, -v11, v14, v13
	v_div_fmas_f32 v11, v11, v12, v14
	v_div_fixup_f32 v10, v11, v1, v98
	s_waitcnt vmcnt(15)
	v_pk_fma_f32 v[6:7], v[96:97], v[10:11], v[166:167] op_sel_hi:[1,0,1]
	v_pk_fma_f32 v[4:5], v[94:95], v[10:11], v[164:165] op_sel_hi:[1,0,1]
	v_mov_b32_e32 v1, v122
	v_cvt_pk_bf16_f32 v4, v4, v5
	v_cvt_pk_bf16_f32 v5, v6, v7
	global_store_dwordx2 v[8:9], v[4:5], off
	s_waitcnt vmcnt(15)
	v_pk_fma_f32 v[6:7], v[92:93], v[10:11], v[170:171] op_sel_hi:[1,0,1]
	v_pk_fma_f32 v[4:5], v[90:91], v[10:11], v[168:169] op_sel_hi:[1,0,1]
	s_nop 0
	v_cvt_pk_bf16_f32 v4, v4, v5
	v_cvt_pk_bf16_f32 v5, v6, v7
	global_store_dwordx2 v[8:9], v[4:5], off offset:32
	s_waitcnt vmcnt(15)
	v_pk_fma_f32 v[6:7], v[88:89], v[10:11], v[174:175] op_sel_hi:[1,0,1]
	v_pk_fma_f32 v[4:5], v[86:87], v[10:11], v[172:173] op_sel_hi:[1,0,1]
	s_nop 0
	v_cvt_pk_bf16_f32 v4, v4, v5
	v_cvt_pk_bf16_f32 v5, v6, v7
	global_store_dwordx2 v[8:9], v[4:5], off offset:64
	s_waitcnt vmcnt(15)
	v_pk_fma_f32 v[6:7], v[84:85], v[10:11], v[178:179] op_sel_hi:[1,0,1]
	v_pk_fma_f32 v[4:5], v[82:83], v[10:11], v[176:177] op_sel_hi:[1,0,1]
	s_nop 0
	v_cvt_pk_bf16_f32 v4, v4, v5
	v_cvt_pk_bf16_f32 v5, v6, v7
	global_store_dwordx2 v[8:9], v[4:5], off offset:96
	s_nop 1
	v_permlane16_swap_b32 v122, v1
	s_nop 0
	v_add_f32_e32 v1, v122, v1
	v_mov_b32_e32 v8, v1
	s_nop 1
	v_permlane32_swap_b32 v8, v1
	v_add_f32_e32 v1, v8, v1
	v_max_f32_e32 v1, 0xda24260, v1
	v_lshl_add_u64 v[8:9], v[2:3], 0, s[62:63]
	s_waitcnt vmcnt(16)
	v_div_scale_f32 v11, s[0:1], v1, v1, v99
	v_rcp_f32_e32 v12, v11
	v_div_scale_f32 v13, vcc, v99, v1, v99
	v_fma_f32 v14, -v11, v12, 1.0
	v_fmac_f32_e32 v12, v14, v12
	v_mul_f32_e32 v14, v13, v12
	v_fma_f32 v15, -v11, v14, v13
	v_fmac_f32_e32 v14, v15, v12
	v_fma_f32 v11, -v11, v14, v13
	v_div_fmas_f32 v11, v11, v12, v14
	v_div_fixup_f32 v10, v11, v1, v99
	s_waitcnt vmcnt(15)
	v_pk_fma_f32 v[6:7], v[80:81], v[10:11], v[182:183] op_sel_hi:[1,0,1]
	v_pk_fma_f32 v[4:5], v[78:79], v[10:11], v[180:181] op_sel_hi:[1,0,1]
	v_mov_b32_e32 v1, v121
	v_cvt_pk_bf16_f32 v4, v4, v5
	v_cvt_pk_bf16_f32 v5, v6, v7
	global_store_dwordx2 v[8:9], v[4:5], off
	s_waitcnt vmcnt(15)
	v_pk_fma_f32 v[6:7], v[76:77], v[10:11], v[186:187] op_sel_hi:[1,0,1]
	v_pk_fma_f32 v[4:5], v[74:75], v[10:11], v[184:185] op_sel_hi:[1,0,1]
	s_nop 0
	v_cvt_pk_bf16_f32 v4, v4, v5
	v_cvt_pk_bf16_f32 v5, v6, v7
	global_store_dwordx2 v[8:9], v[4:5], off offset:32
	s_waitcnt vmcnt(15)
	v_pk_fma_f32 v[6:7], v[72:73], v[10:11], v[190:191] op_sel_hi:[1,0,1]
	v_pk_fma_f32 v[4:5], v[70:71], v[10:11], v[188:189] op_sel_hi:[1,0,1]
	s_nop 0
	v_cvt_pk_bf16_f32 v4, v4, v5
	v_cvt_pk_bf16_f32 v5, v6, v7
	global_store_dwordx2 v[8:9], v[4:5], off offset:64
	s_waitcnt vmcnt(15)
	v_pk_fma_f32 v[6:7], v[68:69], v[10:11], v[194:195] op_sel_hi:[1,0,1]
	v_pk_fma_f32 v[4:5], v[66:67], v[10:11], v[192:193] op_sel_hi:[1,0,1]
	s_nop 0
	v_cvt_pk_bf16_f32 v4, v4, v5
	v_cvt_pk_bf16_f32 v5, v6, v7
	global_store_dwordx2 v[8:9], v[4:5], off offset:96
	s_nop 1
	v_permlane16_swap_b32 v121, v1
	s_nop 0
	v_add_f32_e32 v1, v121, v1
	v_mov_b32_e32 v8, v1
	s_nop 1
	v_permlane32_swap_b32 v8, v1
	v_add_f32_e32 v1, v8, v1
	v_max_f32_e32 v1, 0xda24260, v1
	v_lshl_add_u64 v[8:9], v[2:3], 0, s[60:61]
	s_waitcnt vmcnt(16)
	v_div_scale_f32 v11, s[0:1], v1, v1, v100
	v_rcp_f32_e32 v12, v11
	v_div_scale_f32 v13, vcc, v100, v1, v100
	v_fma_f32 v14, -v11, v12, 1.0
	v_fmac_f32_e32 v12, v14, v12
	v_mul_f32_e32 v14, v13, v12
	v_fma_f32 v15, -v11, v14, v13
	v_fmac_f32_e32 v14, v15, v12
	v_fma_f32 v11, -v11, v14, v13
	v_div_fmas_f32 v11, v11, v12, v14
	v_div_fixup_f32 v10, v11, v1, v100
	s_waitcnt vmcnt(15)
	v_pk_fma_f32 v[6:7], v[64:65], v[10:11], v[198:199] op_sel_hi:[1,0,1]
	v_pk_fma_f32 v[4:5], v[62:63], v[10:11], v[196:197] op_sel_hi:[1,0,1]
	v_mov_b32_e32 v1, v120
	v_cvt_pk_bf16_f32 v4, v4, v5
	v_cvt_pk_bf16_f32 v5, v6, v7
	global_store_dwordx2 v[8:9], v[4:5], off
	s_waitcnt vmcnt(15)
	v_pk_fma_f32 v[6:7], v[60:61], v[10:11], v[202:203] op_sel_hi:[1,0,1]
	v_pk_fma_f32 v[4:5], v[58:59], v[10:11], v[200:201] op_sel_hi:[1,0,1]
	s_nop 0
	v_cvt_pk_bf16_f32 v4, v4, v5
	v_cvt_pk_bf16_f32 v5, v6, v7
	global_store_dwordx2 v[8:9], v[4:5], off offset:32
	s_waitcnt vmcnt(15)
	v_pk_fma_f32 v[6:7], v[56:57], v[10:11], v[206:207] op_sel_hi:[1,0,1]
	v_pk_fma_f32 v[4:5], v[54:55], v[10:11], v[204:205] op_sel_hi:[1,0,1]
	s_nop 0
	v_cvt_pk_bf16_f32 v4, v4, v5
	v_cvt_pk_bf16_f32 v5, v6, v7
	global_store_dwordx2 v[8:9], v[4:5], off offset:64
	s_waitcnt vmcnt(15)
	v_pk_fma_f32 v[6:7], v[52:53], v[10:11], v[210:211] op_sel_hi:[1,0,1]
	v_pk_fma_f32 v[4:5], v[50:51], v[10:11], v[208:209] op_sel_hi:[1,0,1]
	s_nop 0
	v_cvt_pk_bf16_f32 v4, v4, v5
	v_cvt_pk_bf16_f32 v5, v6, v7
	global_store_dwordx2 v[8:9], v[4:5], off offset:96
	s_nop 1
	v_permlane16_swap_b32 v120, v1
	s_nop 0
	v_add_f32_e32 v1, v120, v1
	v_mov_b32_e32 v8, v1
	s_nop 1
	v_permlane32_swap_b32 v1, v8
	v_add_f32_e32 v1, v1, v8
	v_max_f32_e32 v1, 0xda24260, v1
	v_lshl_add_u64 v[8:9], v[2:3], 0, s[58:59]
	s_waitcnt vmcnt(16)
	v_div_scale_f32 v11, s[0:1], v1, v1, v101
	v_rcp_f32_e32 v12, v11
	v_div_scale_f32 v2, vcc, v101, v1, v101
	v_fma_f32 v3, -v11, v12, 1.0
	v_fmac_f32_e32 v12, v3, v12
	v_mul_f32_e32 v3, v2, v12
	v_fma_f32 v13, -v11, v3, v2
	v_fmac_f32_e32 v3, v13, v12
	v_fma_f32 v2, -v11, v3, v2
	v_div_fmas_f32 v2, v2, v12, v3
	v_div_fixup_f32 v10, v2, v1, v101
	s_waitcnt vmcnt(15)
	v_pk_fma_f32 v[2:3], v[48:49], v[10:11], v[230:231] op_sel_hi:[1,0,1]
	v_pk_fma_f32 v[4:5], v[46:47], v[10:11], v[228:229] op_sel_hi:[1,0,1]
	s_nop 0
	v_cvt_pk_bf16_f32 v4, v4, v5
	v_cvt_pk_bf16_f32 v5, v2, v3
	global_store_dwordx2 v[8:9], v[4:5], off
	s_waitcnt vmcnt(15)
	v_pk_fma_f32 v[4:5], v[44:45], v[10:11], v[234:235] op_sel_hi:[1,0,1]
	v_pk_fma_f32 v[2:3], v[42:43], v[10:11], v[232:233] op_sel_hi:[1,0,1]
	s_nop 0
	v_cvt_pk_bf16_f32 v2, v2, v3
	v_cvt_pk_bf16_f32 v3, v4, v5
	global_store_dwordx2 v[8:9], v[2:3], off offset:32
	s_waitcnt vmcnt(15)
	v_pk_fma_f32 v[4:5], v[40:41], v[10:11], v[238:239] op_sel_hi:[1,0,1]
	v_pk_fma_f32 v[2:3], v[38:39], v[10:11], v[236:237] op_sel_hi:[1,0,1]
	s_nop 0
	v_cvt_pk_bf16_f32 v2, v2, v3
	v_cvt_pk_bf16_f32 v3, v4, v5
	global_store_dwordx2 v[8:9], v[2:3], off offset:64
	s_waitcnt vmcnt(15)
	v_pk_fma_f32 v[4:5], v[36:37], v[10:11], v[242:243] op_sel_hi:[1,0,1]
	v_pk_fma_f32 v[2:3], v[34:35], v[10:11], v[240:241] op_sel_hi:[1,0,1]
	s_nop 0
	v_cvt_pk_bf16_f32 v2, v2, v3
	v_cvt_pk_bf16_f32 v3, v4, v5
	global_store_dwordx2 v[8:9], v[2:3], off offset:96
	s_barrier
